# rwkv scans: operand loads issued in need order with per-use counted lgkmcnt waits (4 per step) instead of one wait at the step start; DUAL identity rows decayed early
# baseline (speedup 1.0000x reference)
; template <bool DUAL>
; __device__ __forceinline__ void rwkv_tile(const Params& p, int l, int tile, unsigned char* smem) {
;     ...
;       for (int i = 0; i < 32; ++i) {
;         const int inx = (i + 1) & 31;
;         const float4 nw4 = *(const float4*)(rp + inx * 384), nkk4 = *(const float4*)(rp + inx * 384 + 64), nkb4 = *(const float4*)(rp + inx * 384 + 128);
;         const float4 nkd4 = *(const float4*)(rp + inx * 384 + 192), nr4 = *(const float4*)(rp + inx * 384 + 256);
;         const float nv = vp[inx * 384];
;         v2f t = sA * (v2f){kk4.x, kk4.y};
;         t = sB * (v2f){kk4.z, kk4.w} + t;
;         float sa = t.x + t.y, ia = 0.f;
;         if (DUAL) {
;           v2f ti = iA * (v2f){kk4.x, kk4.y};
;           ti = iB * (v2f){kk4.z, kk4.w} + ti;
;           ia = ti.x + ti.y;
;           sa += dppf<0xB1>(sa); ia += dppf<0xB1>(ia);
;           sa += dppf<0x4E>(sa); ia += dppf<0x4E>(ia);
;           sa += dppf<0x141>(sa); ia += dppf<0x141>(ia);
;           sa += dppf<0x140>(sa); ia += dppf<0x140>(ia);
;         } else {
;           sa = sum16(sa);
;         }
;         v2f cA = sA * (v2f){w4.x, w4.y} + (v2f){kd4.x, kd4.y} * v;
;         v2f cB = sB * (v2f){w4.z, w4.w} + (v2f){kd4.z, kd4.w} * v;
;         sA = cA - (v2f){kb4.x, kb4.y} * sa;
;         sB = cB - (v2f){kb4.z, kb4.w} * sa;
;         v2f u = sA * (v2f){r4.x, r4.y};
;         u = sB * (v2f){r4.z, r4.w} + u;
;         float y = u.x + u.y, g = 0.f;
;         if (DUAL) {
;           iA = iA * (v2f){w4.x, w4.y} - (v2f){kb4.x, kb4.y} * ia;
;           iB = iB * (v2f){w4.z, w4.w} - (v2f){kb4.z, kb4.w} * ia;
;           v2f ui = iA * (v2f){r4.x, r4.y};
;           ui = iB * (v2f){r4.z, r4.w} + ui;
;           g = ui.x + ui.y;
;           y += dppf<0xB1>(y); g += dppf<0xB1>(g);
;           y += dppf<0x4E>(y); g += dppf<0x4E>(g);
;           y += dppf<0x141>(y); g += dppf<0x141>(g);
;           y += dppf<0x140>(y); g += dppf<0x140>(g);
.Lrw_du_loop:
	s_waitcnt lgkmcnt(10)
	v_pk_mul_f32 v[60:61], v[94:95], v[220:221]
	v_pk_mul_f32 v[62:63], v[88:89], v[220:221]
	v_pk_fma_f32 v[60:61], v[92:93], v[222:223], v[60:61]
	v_pk_fma_f32 v[62:63], v[90:91], v[222:223], v[62:63]
	v_add_f32_e32 v60, v60, v61
	v_add_f32_e32 v62, v62, v63
	v_pk_mul_f32 v[94:95], v[94:95], v[216:217]
	v_pk_mul_f32 v[92:93], v[92:93], v[218:219]
	v_add_f32_dpp v60, v60, v60 quad_perm:[1,0,3,2] row_mask:0xf bank_mask:0xf bound_ctrl:1
	v_add_f32_dpp v62, v62, v62 quad_perm:[1,0,3,2] row_mask:0xf bank_mask:0xf bound_ctrl:1
	v_pk_mul_f32 v[88:89], v[88:89], v[216:217]
	v_add_f32_dpp v60, v60, v60 quad_perm:[2,3,0,1] row_mask:0xf bank_mask:0xf bound_ctrl:1
	v_add_f32_dpp v62, v62, v62 quad_perm:[2,3,0,1] row_mask:0xf bank_mask:0xf bound_ctrl:1
	v_pk_mul_f32 v[90:91], v[90:91], v[218:219]
	s_waitcnt lgkmcnt(8)
	v_add_f32_dpp v60, v60, v60 row_half_mirror row_mask:0xf bank_mask:0xf bound_ctrl:1
	v_add_f32_dpp v62, v62, v62 row_half_mirror row_mask:0xf bank_mask:0xf bound_ctrl:1
	v_pk_fma_f32 v[94:95], v[236:237], v[228:229], v[94:95] op_sel_hi:[0,1,1]
	v_add_f32_dpp v60, v60, v60 row_mirror row_mask:0xf bank_mask:0xf bound_ctrl:1
	v_add_f32_dpp v62, v62, v62 row_mirror row_mask:0xf bank_mask:0xf bound_ctrl:1
	v_pk_fma_f32 v[92:93], v[236:237], v[230:231], v[92:93] op_sel_hi:[0,1,1]
	ds_read_b128 v[220:223], v74 offset:28672
	ds_read_b128 v[216:219], v74 offset:28416
	ds_read_b128 v[228:231], v74 offset:29184
	ds_read_b32 v236, v75 offset:29696
	s_waitcnt lgkmcnt(11)
	v_pk_fma_f32 v[94:95], v[224:225], v[60:61], v[94:95] op_sel_hi:[1,0,1] neg_lo:[1,0,0] neg_hi:[1,0,0]
	v_pk_fma_f32 v[92:93], v[226:227], v[60:61], v[92:93] op_sel_hi:[1,0,1] neg_lo:[1,0,0] neg_hi:[1,0,0]
	v_pk_fma_f32 v[88:89], v[224:225], v[62:63], v[88:89] op_sel_hi:[1,0,1] neg_lo:[1,0,0] neg_hi:[1,0,0]
	v_pk_fma_f32 v[90:91], v[226:227], v[62:63], v[90:91] op_sel_hi:[1,0,1] neg_lo:[1,0,0] neg_hi:[1,0,0]
	ds_read_b128 v[224:227], v74 offset:28928
	s_waitcnt lgkmcnt(11)
	v_pk_mul_f32 v[64:65], v[232:233], v[94:95]
	v_pk_fma_f32 v[64:65], v[234:235], v[92:93], v[64:65]
	v_pk_mul_f32 v[66:67], v[232:233], v[88:89]
	v_pk_fma_f32 v[66:67], v[234:235], v[90:91], v[66:67]
	ds_read_b128 v[232:235], v74 offset:29440
	v_add_f32_e32 v144, v64, v65
	v_add_f32_e32 v165, v66, v67
	s_waitcnt lgkmcnt(10)
	v_pk_mul_f32 v[60:61], v[94:95], v[126:127]
	v_pk_mul_f32 v[62:63], v[88:89], v[126:127]
	v_pk_fma_f32 v[60:61], v[92:93], v[128:129], v[60:61]
	v_pk_fma_f32 v[62:63], v[90:91], v[128:129], v[62:63]
	v_add_f32_e32 v60, v60, v61
	v_add_f32_e32 v62, v62, v63
	v_pk_mul_f32 v[94:95], v[94:95], v[122:123]
	v_pk_mul_f32 v[92:93], v[92:93], v[124:125]
	v_add_f32_dpp v60, v60, v60 quad_perm:[1,0,3,2] row_mask:0xf bank_mask:0xf bound_ctrl:1
	v_add_f32_dpp v62, v62, v62 quad_perm:[1,0,3,2] row_mask:0xf bank_mask:0xf bound_ctrl:1
	v_pk_mul_f32 v[88:89], v[88:89], v[122:123]
	v_add_f32_dpp v60, v60, v60 quad_perm:[2,3,0,1] row_mask:0xf bank_mask:0xf bound_ctrl:1
	v_add_f32_dpp v62, v62, v62 quad_perm:[2,3,0,1] row_mask:0xf bank_mask:0xf bound_ctrl:1
	v_pk_mul_f32 v[90:91], v[90:91], v[124:125]
	s_waitcnt lgkmcnt(8)
	v_add_f32_dpp v60, v60, v60 row_half_mirror row_mask:0xf bank_mask:0xf bound_ctrl:1
	v_add_f32_dpp v62, v62, v62 row_half_mirror row_mask:0xf bank_mask:0xf bound_ctrl:1
	v_pk_fma_f32 v[94:95], v[142:143], v[134:135], v[94:95] op_sel_hi:[0,1,1]
	v_add_f32_dpp v60, v60, v60 row_mirror row_mask:0xf bank_mask:0xf bound_ctrl:1
	v_add_f32_dpp v62, v62, v62 row_mirror row_mask:0xf bank_mask:0xf bound_ctrl:1
	v_pk_fma_f32 v[92:93], v[142:143], v[136:137], v[92:93] op_sel_hi:[0,1,1]
	ds_read_b128 v[126:129], v74 offset:30208
	ds_read_b128 v[122:125], v74 offset:29952
	ds_read_b128 v[134:137], v74 offset:30720
	ds_read_b32 v142, v75 offset:31232
	s_waitcnt lgkmcnt(11)
	v_pk_fma_f32 v[94:95], v[130:131], v[60:61], v[94:95] op_sel_hi:[1,0,1] neg_lo:[1,0,0] neg_hi:[1,0,0]
	v_pk_fma_f32 v[92:93], v[132:133], v[60:61], v[92:93] op_sel_hi:[1,0,1] neg_lo:[1,0,0] neg_hi:[1,0,0]
	v_pk_fma_f32 v[88:89], v[130:131], v[62:63], v[88:89] op_sel_hi:[1,0,1] neg_lo:[1,0,0] neg_hi:[1,0,0]
	v_pk_fma_f32 v[90:91], v[132:133], v[62:63], v[90:91] op_sel_hi:[1,0,1] neg_lo:[1,0,0] neg_hi:[1,0,0]
	ds_read_b128 v[130:133], v74 offset:30464
	s_waitcnt lgkmcnt(11)
	v_pk_mul_f32 v[64:65], v[138:139], v[94:95]
	v_pk_fma_f32 v[64:65], v[140:141], v[92:93], v[64:65]
	v_pk_mul_f32 v[66:67], v[138:139], v[88:89]
	v_pk_fma_f32 v[66:67], v[140:141], v[90:91], v[66:67]
	ds_read_b128 v[138:141], v74 offset:30976
	v_add_f32_e32 v145, v64, v65
	v_add_f32_e32 v166, v66, v67
	s_waitcnt lgkmcnt(10)
	v_pk_mul_f32 v[60:61], v[94:95], v[220:221]
	v_pk_mul_f32 v[62:63], v[88:89], v[220:221]
	v_pk_fma_f32 v[60:61], v[92:93], v[222:223], v[60:61]
	v_pk_fma_f32 v[62:63], v[90:91], v[222:223], v[62:63]
	v_add_f32_e32 v60, v60, v61
	v_add_f32_e32 v62, v62, v63
	v_pk_mul_f32 v[94:95], v[94:95], v[216:217]
	v_pk_mul_f32 v[92:93], v[92:93], v[218:219]
	v_add_f32_dpp v60, v60, v60 quad_perm:[1,0,3,2] row_mask:0xf bank_mask:0xf bound_ctrl:1
	v_add_f32_dpp v62, v62, v62 quad_perm:[1,0,3,2] row_mask:0xf bank_mask:0xf bound_ctrl:1
	v_pk_mul_f32 v[88:89], v[88:89], v[216:217]
	v_add_f32_dpp v60, v60, v60 quad_perm:[2,3,0,1] row_mask:0xf bank_mask:0xf bound_ctrl:1
	v_add_f32_dpp v62, v62, v62 quad_perm:[2,3,0,1] row_mask:0xf bank_mask:0xf bound_ctrl:1
	v_pk_mul_f32 v[90:91], v[90:91], v[218:219]
	s_waitcnt lgkmcnt(8)
; template <bool DUAL>
; __device__ __forceinline__ void rwkv_tile(const Params& p, int l, int tile, unsigned char* smem) {
;     ...
;       for (int i = 0; i < 32; ++i) {
;         const int inx = (i + 1) & 31;
;         const float4 nw4 = *(const float4*)(rp + inx * 384), nkk4 = *(const float4*)(rp + inx * 384 + 64), nkb4 = *(const float4*)(rp + inx * 384 + 128);
;         const float4 nkd4 = *(const float4*)(rp + inx * 384 + 192), nr4 = *(const float4*)(rp + inx * 384 + 256);
;         const float nv = vp[inx * 384];
;         v2f t = sA * (v2f){kk4.x, kk4.y};
;         t = sB * (v2f){kk4.z, kk4.w} + t;
;         float sa = t.x + t.y, ia = 0.f;
;         if (DUAL) {
;           v2f ti = iA * (v2f){kk4.x, kk4.y};
;           ti = iB * (v2f){kk4.z, kk4.w} + ti;
;           ia = ti.x + ti.y;
;           sa += dppf<0xB1>(sa); ia += dppf<0xB1>(ia);
;           sa += dppf<0x4E>(sa); ia += dppf<0x4E>(ia);
;           sa += dppf<0x141>(sa); ia += dppf<0x141>(ia);
;           sa += dppf<0x140>(sa); ia += dppf<0x140>(ia);
;         } else {
;           sa = sum16(sa);
;         }
;         v2f cA = sA * (v2f){w4.x, w4.y} + (v2f){kd4.x, kd4.y} * v;
;         v2f cB = sB * (v2f){w4.z, w4.w} + (v2f){kd4.z, kd4.w} * v;
;         sA = cA - (v2f){kb4.x, kb4.y} * sa;
;         sB = cB - (v2f){kb4.z, kb4.w} * sa;
;         v2f u = sA * (v2f){r4.x, r4.y};
;         u = sB * (v2f){r4.z, r4.w} + u;
;         float y = u.x + u.y, g = 0.f;
;         if (DUAL) {
;           iA = iA * (v2f){w4.x, w4.y} - (v2f){kb4.x, kb4.y} * ia;
;           iB = iB * (v2f){w4.z, w4.w} - (v2f){kb4.z, kb4.w} * ia;
;           v2f ui = iA * (v2f){r4.x, r4.y};
;           ui = iB * (v2f){r4.z, r4.w} + ui;
;           g = ui.x + ui.y;
;           y += dppf<0xB1>(y); g += dppf<0xB1>(g);
;           y += dppf<0x4E>(y); g += dppf<0x4E>(g);
;           y += dppf<0x141>(y); g += dppf<0x141>(g);
;           y += dppf<0x140>(y); g += dppf<0x140>(g);
	v_add_f32_dpp v60, v60, v60 row_half_mirror row_mask:0xf bank_mask:0xf bound_ctrl:1
	v_add_f32_dpp v62, v62, v62 row_half_mirror row_mask:0xf bank_mask:0xf bound_ctrl:1
	v_pk_fma_f32 v[94:95], v[236:237], v[228:229], v[94:95] op_sel_hi:[0,1,1]
	v_add_f32_dpp v60, v60, v60 row_mirror row_mask:0xf bank_mask:0xf bound_ctrl:1
	v_add_f32_dpp v62, v62, v62 row_mirror row_mask:0xf bank_mask:0xf bound_ctrl:1
	v_pk_fma_f32 v[92:93], v[236:237], v[230:231], v[92:93] op_sel_hi:[0,1,1]
	ds_read_b128 v[220:223], v74 offset:31744
	ds_read_b128 v[216:219], v74 offset:31488
	ds_read_b128 v[228:231], v74 offset:32256
	ds_read_b32 v236, v75 offset:32768
	s_waitcnt lgkmcnt(11)
	v_pk_fma_f32 v[94:95], v[224:225], v[60:61], v[94:95] op_sel_hi:[1,0,1] neg_lo:[1,0,0] neg_hi:[1,0,0]
	v_pk_fma_f32 v[92:93], v[226:227], v[60:61], v[92:93] op_sel_hi:[1,0,1] neg_lo:[1,0,0] neg_hi:[1,0,0]
	v_pk_fma_f32 v[88:89], v[224:225], v[62:63], v[88:89] op_sel_hi:[1,0,1] neg_lo:[1,0,0] neg_hi:[1,0,0]
	v_pk_fma_f32 v[90:91], v[226:227], v[62:63], v[90:91] op_sel_hi:[1,0,1] neg_lo:[1,0,0] neg_hi:[1,0,0]
	ds_read_b128 v[224:227], v74 offset:32000
	s_waitcnt lgkmcnt(11)
	v_pk_mul_f32 v[64:65], v[232:233], v[94:95]
	v_pk_fma_f32 v[64:65], v[234:235], v[92:93], v[64:65]
	v_pk_mul_f32 v[66:67], v[232:233], v[88:89]
	v_pk_fma_f32 v[66:67], v[234:235], v[90:91], v[66:67]
	ds_read_b128 v[232:235], v74 offset:32512
	v_add_f32_e32 v146, v64, v65
	v_add_f32_e32 v167, v66, v67
	s_waitcnt lgkmcnt(10)
	v_pk_mul_f32 v[60:61], v[94:95], v[126:127]
	v_pk_mul_f32 v[62:63], v[88:89], v[126:127]
	v_pk_fma_f32 v[60:61], v[92:93], v[128:129], v[60:61]
	v_pk_fma_f32 v[62:63], v[90:91], v[128:129], v[62:63]
	v_add_f32_e32 v60, v60, v61
	v_add_f32_e32 v62, v62, v63
	v_pk_mul_f32 v[94:95], v[94:95], v[122:123]
	v_pk_mul_f32 v[92:93], v[92:93], v[124:125]
	v_add_f32_dpp v60, v60, v60 quad_perm:[1,0,3,2] row_mask:0xf bank_mask:0xf bound_ctrl:1
	v_add_f32_dpp v62, v62, v62 quad_perm:[1,0,3,2] row_mask:0xf bank_mask:0xf bound_ctrl:1
	v_pk_mul_f32 v[88:89], v[88:89], v[122:123]
	v_add_f32_dpp v60, v60, v60 quad_perm:[2,3,0,1] row_mask:0xf bank_mask:0xf bound_ctrl:1
	v_add_f32_dpp v62, v62, v62 quad_perm:[2,3,0,1] row_mask:0xf bank_mask:0xf bound_ctrl:1
	v_pk_mul_f32 v[90:91], v[90:91], v[124:125]
	s_waitcnt lgkmcnt(8)
	v_add_f32_dpp v60, v60, v60 row_half_mirror row_mask:0xf bank_mask:0xf bound_ctrl:1
	v_add_f32_dpp v62, v62, v62 row_half_mirror row_mask:0xf bank_mask:0xf bound_ctrl:1
	v_pk_fma_f32 v[94:95], v[142:143], v[134:135], v[94:95] op_sel_hi:[0,1,1]
	v_add_f32_dpp v60, v60, v60 row_mirror row_mask:0xf bank_mask:0xf bound_ctrl:1
	v_add_f32_dpp v62, v62, v62 row_mirror row_mask:0xf bank_mask:0xf bound_ctrl:1
	v_pk_fma_f32 v[92:93], v[142:143], v[136:137], v[92:93] op_sel_hi:[0,1,1]
	ds_read_b128 v[126:129], v74 offset:33280
	ds_read_b128 v[122:125], v74 offset:33024
	ds_read_b128 v[134:137], v74 offset:33792
	ds_read_b32 v142, v75 offset:34304
	s_waitcnt lgkmcnt(11)
	v_pk_fma_f32 v[94:95], v[130:131], v[60:61], v[94:95] op_sel_hi:[1,0,1] neg_lo:[1,0,0] neg_hi:[1,0,0]
	v_pk_fma_f32 v[92:93], v[132:133], v[60:61], v[92:93] op_sel_hi:[1,0,1] neg_lo:[1,0,0] neg_hi:[1,0,0]
	v_pk_fma_f32 v[88:89], v[130:131], v[62:63], v[88:89] op_sel_hi:[1,0,1] neg_lo:[1,0,0] neg_hi:[1,0,0]
	v_pk_fma_f32 v[90:91], v[132:133], v[62:63], v[90:91] op_sel_hi:[1,0,1] neg_lo:[1,0,0] neg_hi:[1,0,0]
	ds_read_b128 v[130:133], v74 offset:33536
	s_waitcnt lgkmcnt(11)
	v_pk_mul_f32 v[64:65], v[138:139], v[94:95]
	v_pk_fma_f32 v[64:65], v[140:141], v[92:93], v[64:65]
	v_pk_mul_f32 v[66:67], v[138:139], v[88:89]
	v_pk_fma_f32 v[66:67], v[140:141], v[90:91], v[66:67]
	ds_read_b128 v[138:141], v74 offset:34048
	v_add_f32_e32 v147, v64, v65
	v_add_f32_e32 v168, v66, v67
	s_waitcnt lgkmcnt(10)
	v_pk_mul_f32 v[60:61], v[94:95], v[220:221]
	v_pk_mul_f32 v[62:63], v[88:89], v[220:221]
	v_pk_fma_f32 v[60:61], v[92:93], v[222:223], v[60:61]
	v_pk_fma_f32 v[62:63], v[90:91], v[222:223], v[62:63]
	v_add_f32_e32 v60, v60, v61
	v_add_f32_e32 v62, v62, v63
	v_pk_mul_f32 v[94:95], v[94:95], v[216:217]
	v_pk_mul_f32 v[92:93], v[92:93], v[218:219]
	v_add_f32_dpp v60, v60, v60 quad_perm:[1,0,3,2] row_mask:0xf bank_mask:0xf bound_ctrl:1
	v_add_f32_dpp v62, v62, v62 quad_perm:[1,0,3,2] row_mask:0xf bank_mask:0xf bound_ctrl:1
	v_pk_mul_f32 v[88:89], v[88:89], v[216:217]
	v_add_f32_dpp v60, v60, v60 quad_perm:[2,3,0,1] row_mask:0xf bank_mask:0xf bound_ctrl:1
	v_add_f32_dpp v62, v62, v62 quad_perm:[2,3,0,1] row_mask:0xf bank_mask:0xf bound_ctrl:1
	v_pk_mul_f32 v[90:91], v[90:91], v[218:219]
	s_waitcnt lgkmcnt(8)
	v_add_f32_dpp v60, v60, v60 row_half_mirror row_mask:0xf bank_mask:0xf bound_ctrl:1
	v_add_f32_dpp v62, v62, v62 row_half_mirror row_mask:0xf bank_mask:0xf bound_ctrl:1
	v_pk_fma_f32 v[94:95], v[236:237], v[228:229], v[94:95] op_sel_hi:[0,1,1]
	v_add_f32_dpp v60, v60, v60 row_mirror row_mask:0xf bank_mask:0xf bound_ctrl:1
	v_add_f32_dpp v62, v62, v62 row_mirror row_mask:0xf bank_mask:0xf bound_ctrl:1
	v_pk_fma_f32 v[92:93], v[236:237], v[230:231], v[92:93] op_sel_hi:[0,1,1]
	ds_read_b128 v[220:223], v74 offset:34816
	ds_read_b128 v[216:219], v74 offset:34560
	ds_read_b128 v[228:231], v74 offset:35328
	ds_read_b32 v236, v75 offset:35840
	s_waitcnt lgkmcnt(11)
	v_pk_fma_f32 v[94:95], v[224:225], v[60:61], v[94:95] op_sel_hi:[1,0,1] neg_lo:[1,0,0] neg_hi:[1,0,0]
	v_pk_fma_f32 v[92:93], v[226:227], v[60:61], v[92:93] op_sel_hi:[1,0,1] neg_lo:[1,0,0] neg_hi:[1,0,0]
	v_pk_fma_f32 v[88:89], v[224:225], v[62:63], v[88:89] op_sel_hi:[1,0,1] neg_lo:[1,0,0] neg_hi:[1,0,0]
	v_pk_fma_f32 v[90:91], v[226:227], v[62:63], v[90:91] op_sel_hi:[1,0,1] neg_lo:[1,0,0] neg_hi:[1,0,0]
	ds_read_b128 v[224:227], v74 offset:35072
	s_waitcnt lgkmcnt(11)
; template <bool DUAL>
; __device__ __forceinline__ void rwkv_tile(const Params& p, int l, int tile, unsigned char* smem) {
;     ...
;       for (int i = 0; i < 32; ++i) {
;         const int inx = (i + 1) & 31;
;         const float4 nw4 = *(const float4*)(rp + inx * 384), nkk4 = *(const float4*)(rp + inx * 384 + 64), nkb4 = *(const float4*)(rp + inx * 384 + 128);
;         const float4 nkd4 = *(const float4*)(rp + inx * 384 + 192), nr4 = *(const float4*)(rp + inx * 384 + 256);
;         const float nv = vp[inx * 384];
;         v2f t = sA * (v2f){kk4.x, kk4.y};
;         t = sB * (v2f){kk4.z, kk4.w} + t;
;         float sa = t.x + t.y, ia = 0.f;
;         if (DUAL) {
;           v2f ti = iA * (v2f){kk4.x, kk4.y};
;           ti = iB * (v2f){kk4.z, kk4.w} + ti;
;           ia = ti.x + ti.y;
;           sa += dppf<0xB1>(sa); ia += dppf<0xB1>(ia);
;           sa += dppf<0x4E>(sa); ia += dppf<0x4E>(ia);
;           sa += dppf<0x141>(sa); ia += dppf<0x141>(ia);
;           sa += dppf<0x140>(sa); ia += dppf<0x140>(ia);
;         } else {
;           sa = sum16(sa);
;         }
;         v2f cA = sA * (v2f){w4.x, w4.y} + (v2f){kd4.x, kd4.y} * v;
;         v2f cB = sB * (v2f){w4.z, w4.w} + (v2f){kd4.z, kd4.w} * v;
;         sA = cA - (v2f){kb4.x, kb4.y} * sa;
;         sB = cB - (v2f){kb4.z, kb4.w} * sa;
;         v2f u = sA * (v2f){r4.x, r4.y};
;         u = sB * (v2f){r4.z, r4.w} + u;
;         float y = u.x + u.y, g = 0.f;
;         if (DUAL) {
;           iA = iA * (v2f){w4.x, w4.y} - (v2f){kb4.x, kb4.y} * ia;
;           iB = iB * (v2f){w4.z, w4.w} - (v2f){kb4.z, kb4.w} * ia;
;           v2f ui = iA * (v2f){r4.x, r4.y};
;           ui = iB * (v2f){r4.z, r4.w} + ui;
;           g = ui.x + ui.y;
;           y += dppf<0xB1>(y); g += dppf<0xB1>(g);
;           y += dppf<0x4E>(y); g += dppf<0x4E>(g);
;           y += dppf<0x141>(y); g += dppf<0x141>(g);
;           y += dppf<0x140>(y); g += dppf<0x140>(g);
	v_pk_mul_f32 v[64:65], v[232:233], v[94:95]
	v_pk_fma_f32 v[64:65], v[234:235], v[92:93], v[64:65]
	v_pk_mul_f32 v[66:67], v[232:233], v[88:89]
	v_pk_fma_f32 v[66:67], v[234:235], v[90:91], v[66:67]
	ds_read_b128 v[232:235], v74 offset:35584
	v_add_f32_e32 v148, v64, v65
	v_add_f32_e32 v169, v66, v67
	s_waitcnt lgkmcnt(10)
	v_pk_mul_f32 v[60:61], v[94:95], v[126:127]
	v_pk_mul_f32 v[62:63], v[88:89], v[126:127]
	v_pk_fma_f32 v[60:61], v[92:93], v[128:129], v[60:61]
	v_pk_fma_f32 v[62:63], v[90:91], v[128:129], v[62:63]
	v_add_f32_e32 v60, v60, v61
	v_add_f32_e32 v62, v62, v63
	v_pk_mul_f32 v[94:95], v[94:95], v[122:123]
	v_pk_mul_f32 v[92:93], v[92:93], v[124:125]
	v_add_f32_dpp v60, v60, v60 quad_perm:[1,0,3,2] row_mask:0xf bank_mask:0xf bound_ctrl:1
	v_add_f32_dpp v62, v62, v62 quad_perm:[1,0,3,2] row_mask:0xf bank_mask:0xf bound_ctrl:1
	v_pk_mul_f32 v[88:89], v[88:89], v[122:123]
	v_add_f32_dpp v60, v60, v60 quad_perm:[2,3,0,1] row_mask:0xf bank_mask:0xf bound_ctrl:1
	v_add_f32_dpp v62, v62, v62 quad_perm:[2,3,0,1] row_mask:0xf bank_mask:0xf bound_ctrl:1
	v_pk_mul_f32 v[90:91], v[90:91], v[124:125]
	s_waitcnt lgkmcnt(8)
	v_add_f32_dpp v60, v60, v60 row_half_mirror row_mask:0xf bank_mask:0xf bound_ctrl:1
	v_add_f32_dpp v62, v62, v62 row_half_mirror row_mask:0xf bank_mask:0xf bound_ctrl:1
	v_pk_fma_f32 v[94:95], v[142:143], v[134:135], v[94:95] op_sel_hi:[0,1,1]
	v_add_f32_dpp v60, v60, v60 row_mirror row_mask:0xf bank_mask:0xf bound_ctrl:1
	v_add_f32_dpp v62, v62, v62 row_mirror row_mask:0xf bank_mask:0xf bound_ctrl:1
	v_pk_fma_f32 v[92:93], v[142:143], v[136:137], v[92:93] op_sel_hi:[0,1,1]
	ds_read_b128 v[126:129], v74 offset:36352
	ds_read_b128 v[122:125], v74 offset:36096
	ds_read_b128 v[134:137], v74 offset:36864
	ds_read_b32 v142, v75 offset:37376
	s_waitcnt lgkmcnt(11)
	v_pk_fma_f32 v[94:95], v[130:131], v[60:61], v[94:95] op_sel_hi:[1,0,1] neg_lo:[1,0,0] neg_hi:[1,0,0]
	v_pk_fma_f32 v[92:93], v[132:133], v[60:61], v[92:93] op_sel_hi:[1,0,1] neg_lo:[1,0,0] neg_hi:[1,0,0]
	v_pk_fma_f32 v[88:89], v[130:131], v[62:63], v[88:89] op_sel_hi:[1,0,1] neg_lo:[1,0,0] neg_hi:[1,0,0]
	v_pk_fma_f32 v[90:91], v[132:133], v[62:63], v[90:91] op_sel_hi:[1,0,1] neg_lo:[1,0,0] neg_hi:[1,0,0]
	ds_read_b128 v[130:133], v74 offset:36608
	s_waitcnt lgkmcnt(11)
	v_pk_mul_f32 v[64:65], v[138:139], v[94:95]
	v_pk_fma_f32 v[64:65], v[140:141], v[92:93], v[64:65]
	v_pk_mul_f32 v[66:67], v[138:139], v[88:89]
	v_pk_fma_f32 v[66:67], v[140:141], v[90:91], v[66:67]
	ds_read_b128 v[138:141], v74 offset:37120
	v_add_f32_e32 v149, v64, v65
	v_add_f32_e32 v170, v66, v67
	s_waitcnt lgkmcnt(10)
	v_pk_mul_f32 v[60:61], v[94:95], v[220:221]
	v_pk_mul_f32 v[62:63], v[88:89], v[220:221]
	v_pk_fma_f32 v[60:61], v[92:93], v[222:223], v[60:61]
	v_pk_fma_f32 v[62:63], v[90:91], v[222:223], v[62:63]
	v_add_f32_e32 v60, v60, v61
	v_add_f32_e32 v62, v62, v63
	v_pk_mul_f32 v[94:95], v[94:95], v[216:217]
	v_pk_mul_f32 v[92:93], v[92:93], v[218:219]
	v_add_f32_dpp v60, v60, v60 quad_perm:[1,0,3,2] row_mask:0xf bank_mask:0xf bound_ctrl:1
	v_add_f32_dpp v62, v62, v62 quad_perm:[1,0,3,2] row_mask:0xf bank_mask:0xf bound_ctrl:1
	v_pk_mul_f32 v[88:89], v[88:89], v[216:217]
	v_add_f32_dpp v60, v60, v60 quad_perm:[2,3,0,1] row_mask:0xf bank_mask:0xf bound_ctrl:1
	v_add_f32_dpp v62, v62, v62 quad_perm:[2,3,0,1] row_mask:0xf bank_mask:0xf bound_ctrl:1
	v_pk_mul_f32 v[90:91], v[90:91], v[218:219]
	s_waitcnt lgkmcnt(8)
	v_add_f32_dpp v60, v60, v60 row_half_mirror row_mask:0xf bank_mask:0xf bound_ctrl:1
	v_add_f32_dpp v62, v62, v62 row_half_mirror row_mask:0xf bank_mask:0xf bound_ctrl:1
	v_pk_fma_f32 v[94:95], v[236:237], v[228:229], v[94:95] op_sel_hi:[0,1,1]
	v_add_f32_dpp v60, v60, v60 row_mirror row_mask:0xf bank_mask:0xf bound_ctrl:1
	v_add_f32_dpp v62, v62, v62 row_mirror row_mask:0xf bank_mask:0xf bound_ctrl:1
	v_pk_fma_f32 v[92:93], v[236:237], v[230:231], v[92:93] op_sel_hi:[0,1,1]
	ds_read_b128 v[220:223], v74 offset:37888
	ds_read_b128 v[216:219], v74 offset:37632
	ds_read_b128 v[228:231], v74 offset:38400
	ds_read_b32 v236, v75 offset:38912
	s_waitcnt lgkmcnt(11)
	v_pk_fma_f32 v[94:95], v[224:225], v[60:61], v[94:95] op_sel_hi:[1,0,1] neg_lo:[1,0,0] neg_hi:[1,0,0]
	v_pk_fma_f32 v[92:93], v[226:227], v[60:61], v[92:93] op_sel_hi:[1,0,1] neg_lo:[1,0,0] neg_hi:[1,0,0]
	v_pk_fma_f32 v[88:89], v[224:225], v[62:63], v[88:89] op_sel_hi:[1,0,1] neg_lo:[1,0,0] neg_hi:[1,0,0]
	v_pk_fma_f32 v[90:91], v[226:227], v[62:63], v[90:91] op_sel_hi:[1,0,1] neg_lo:[1,0,0] neg_hi:[1,0,0]
	ds_read_b128 v[224:227], v74 offset:38144
	s_waitcnt lgkmcnt(11)
	v_pk_mul_f32 v[64:65], v[232:233], v[94:95]
	v_pk_fma_f32 v[64:65], v[234:235], v[92:93], v[64:65]
	v_pk_mul_f32 v[66:67], v[232:233], v[88:89]
	v_pk_fma_f32 v[66:67], v[234:235], v[90:91], v[66:67]
	ds_read_b128 v[232:235], v74 offset:38656
	v_add_f32_e32 v150, v64, v65
	v_add_f32_e32 v171, v66, v67
	s_waitcnt lgkmcnt(10)
	v_pk_mul_f32 v[60:61], v[94:95], v[126:127]
	v_pk_mul_f32 v[62:63], v[88:89], v[126:127]
	v_pk_fma_f32 v[60:61], v[92:93], v[128:129], v[60:61]
	v_pk_fma_f32 v[62:63], v[90:91], v[128:129], v[62:63]
	v_add_f32_e32 v60, v60, v61
	v_add_f32_e32 v62, v62, v63
	v_pk_mul_f32 v[94:95], v[94:95], v[122:123]
	v_pk_mul_f32 v[92:93], v[92:93], v[124:125]
	v_add_f32_dpp v60, v60, v60 quad_perm:[1,0,3,2] row_mask:0xf bank_mask:0xf bound_ctrl:1
	v_add_f32_dpp v62, v62, v62 quad_perm:[1,0,3,2] row_mask:0xf bank_mask:0xf bound_ctrl:1
	v_pk_mul_f32 v[88:89], v[88:89], v[122:123]
	v_add_f32_dpp v60, v60, v60 quad_perm:[2,3,0,1] row_mask:0xf bank_mask:0xf bound_ctrl:1
	v_add_f32_dpp v62, v62, v62 quad_perm:[2,3,0,1] row_mask:0xf bank_mask:0xf bound_ctrl:1
	v_pk_mul_f32 v[90:91], v[90:91], v[124:125]
	s_waitcnt lgkmcnt(8)
; template <bool DUAL>
; __device__ __forceinline__ void rwkv_tile(const Params& p, int l, int tile, unsigned char* smem) {
;     ...
;       for (int i = 0; i < 32; ++i) {
;         const int inx = (i + 1) & 31;
;         const float4 nw4 = *(const float4*)(rp + inx * 384), nkk4 = *(const float4*)(rp + inx * 384 + 64), nkb4 = *(const float4*)(rp + inx * 384 + 128);
;         const float4 nkd4 = *(const float4*)(rp + inx * 384 + 192), nr4 = *(const float4*)(rp + inx * 384 + 256);
;         const float nv = vp[inx * 384];
;         v2f t = sA * (v2f){kk4.x, kk4.y};
;         t = sB * (v2f){kk4.z, kk4.w} + t;
;         float sa = t.x + t.y, ia = 0.f;
;         if (DUAL) {
;           v2f ti = iA * (v2f){kk4.x, kk4.y};
;           ti = iB * (v2f){kk4.z, kk4.w} + ti;
;           ia = ti.x + ti.y;
;           sa += dppf<0xB1>(sa); ia += dppf<0xB1>(ia);
;           sa += dppf<0x4E>(sa); ia += dppf<0x4E>(ia);
;           sa += dppf<0x141>(sa); ia += dppf<0x141>(ia);
;           sa += dppf<0x140>(sa); ia += dppf<0x140>(ia);
;         } else {
;           sa = sum16(sa);
;         }
;         v2f cA = sA * (v2f){w4.x, w4.y} + (v2f){kd4.x, kd4.y} * v;
;         v2f cB = sB * (v2f){w4.z, w4.w} + (v2f){kd4.z, kd4.w} * v;
;         sA = cA - (v2f){kb4.x, kb4.y} * sa;
;         sB = cB - (v2f){kb4.z, kb4.w} * sa;
;         v2f u = sA * (v2f){r4.x, r4.y};
;         u = sB * (v2f){r4.z, r4.w} + u;
;         float y = u.x + u.y, g = 0.f;
;         if (DUAL) {
;           iA = iA * (v2f){w4.x, w4.y} - (v2f){kb4.x, kb4.y} * ia;
;           iB = iB * (v2f){w4.z, w4.w} - (v2f){kb4.z, kb4.w} * ia;
;           v2f ui = iA * (v2f){r4.x, r4.y};
;           ui = iB * (v2f){r4.z, r4.w} + ui;
;           g = ui.x + ui.y;
;           y += dppf<0xB1>(y); g += dppf<0xB1>(g);
;           y += dppf<0x4E>(y); g += dppf<0x4E>(g);
;           y += dppf<0x141>(y); g += dppf<0x141>(g);
;           y += dppf<0x140>(y); g += dppf<0x140>(g);
	v_add_f32_dpp v60, v60, v60 row_half_mirror row_mask:0xf bank_mask:0xf bound_ctrl:1
	v_add_f32_dpp v62, v62, v62 row_half_mirror row_mask:0xf bank_mask:0xf bound_ctrl:1
	v_pk_fma_f32 v[94:95], v[142:143], v[134:135], v[94:95] op_sel_hi:[0,1,1]
	v_add_f32_dpp v60, v60, v60 row_mirror row_mask:0xf bank_mask:0xf bound_ctrl:1
	v_add_f32_dpp v62, v62, v62 row_mirror row_mask:0xf bank_mask:0xf bound_ctrl:1
	v_pk_fma_f32 v[92:93], v[142:143], v[136:137], v[92:93] op_sel_hi:[0,1,1]
	ds_read_b128 v[126:129], v74 offset:39424
	ds_read_b128 v[122:125], v74 offset:39168
	ds_read_b128 v[134:137], v74 offset:39936
	ds_read_b32 v142, v75 offset:40448
	s_waitcnt lgkmcnt(11)
	v_pk_fma_f32 v[94:95], v[130:131], v[60:61], v[94:95] op_sel_hi:[1,0,1] neg_lo:[1,0,0] neg_hi:[1,0,0]
	v_pk_fma_f32 v[92:93], v[132:133], v[60:61], v[92:93] op_sel_hi:[1,0,1] neg_lo:[1,0,0] neg_hi:[1,0,0]
	v_pk_fma_f32 v[88:89], v[130:131], v[62:63], v[88:89] op_sel_hi:[1,0,1] neg_lo:[1,0,0] neg_hi:[1,0,0]
	v_pk_fma_f32 v[90:91], v[132:133], v[62:63], v[90:91] op_sel_hi:[1,0,1] neg_lo:[1,0,0] neg_hi:[1,0,0]
	ds_read_b128 v[130:133], v74 offset:39680
	s_waitcnt lgkmcnt(11)
	v_pk_mul_f32 v[64:65], v[138:139], v[94:95]
	v_pk_fma_f32 v[64:65], v[140:141], v[92:93], v[64:65]
	v_pk_mul_f32 v[66:67], v[138:139], v[88:89]
	v_pk_fma_f32 v[66:67], v[140:141], v[90:91], v[66:67]
	ds_read_b128 v[138:141], v74 offset:40192
	v_add_f32_e32 v151, v64, v65
	v_add_f32_e32 v172, v66, v67
	s_waitcnt lgkmcnt(10)
	v_pk_mul_f32 v[60:61], v[94:95], v[220:221]
	v_pk_mul_f32 v[62:63], v[88:89], v[220:221]
	v_pk_fma_f32 v[60:61], v[92:93], v[222:223], v[60:61]
	v_pk_fma_f32 v[62:63], v[90:91], v[222:223], v[62:63]
	v_add_f32_e32 v60, v60, v61
	v_add_f32_e32 v62, v62, v63
	v_pk_mul_f32 v[94:95], v[94:95], v[216:217]
	v_pk_mul_f32 v[92:93], v[92:93], v[218:219]
	v_add_f32_dpp v60, v60, v60 quad_perm:[1,0,3,2] row_mask:0xf bank_mask:0xf bound_ctrl:1
	v_add_f32_dpp v62, v62, v62 quad_perm:[1,0,3,2] row_mask:0xf bank_mask:0xf bound_ctrl:1
	v_pk_mul_f32 v[88:89], v[88:89], v[216:217]
	v_add_f32_dpp v60, v60, v60 quad_perm:[2,3,0,1] row_mask:0xf bank_mask:0xf bound_ctrl:1
	v_add_f32_dpp v62, v62, v62 quad_perm:[2,3,0,1] row_mask:0xf bank_mask:0xf bound_ctrl:1
	v_pk_mul_f32 v[90:91], v[90:91], v[218:219]
	s_waitcnt lgkmcnt(8)
	v_add_f32_dpp v60, v60, v60 row_half_mirror row_mask:0xf bank_mask:0xf bound_ctrl:1
	v_add_f32_dpp v62, v62, v62 row_half_mirror row_mask:0xf bank_mask:0xf bound_ctrl:1
	v_pk_fma_f32 v[94:95], v[236:237], v[228:229], v[94:95] op_sel_hi:[0,1,1]
	v_add_f32_dpp v60, v60, v60 row_mirror row_mask:0xf bank_mask:0xf bound_ctrl:1
	v_add_f32_dpp v62, v62, v62 row_mirror row_mask:0xf bank_mask:0xf bound_ctrl:1
	v_pk_fma_f32 v[92:93], v[236:237], v[230:231], v[92:93] op_sel_hi:[0,1,1]
	ds_read_b128 v[220:223], v74 offset:40960
	ds_read_b128 v[216:219], v74 offset:40704
	ds_read_b128 v[228:231], v74 offset:41472
	ds_read_b32 v236, v75 offset:41984
	s_waitcnt lgkmcnt(11)
	v_pk_fma_f32 v[94:95], v[224:225], v[60:61], v[94:95] op_sel_hi:[1,0,1] neg_lo:[1,0,0] neg_hi:[1,0,0]
	v_pk_fma_f32 v[92:93], v[226:227], v[60:61], v[92:93] op_sel_hi:[1,0,1] neg_lo:[1,0,0] neg_hi:[1,0,0]
	v_pk_fma_f32 v[88:89], v[224:225], v[62:63], v[88:89] op_sel_hi:[1,0,1] neg_lo:[1,0,0] neg_hi:[1,0,0]
	v_pk_fma_f32 v[90:91], v[226:227], v[62:63], v[90:91] op_sel_hi:[1,0,1] neg_lo:[1,0,0] neg_hi:[1,0,0]
	ds_read_b128 v[224:227], v74 offset:41216
	s_waitcnt lgkmcnt(11)
	v_pk_mul_f32 v[64:65], v[232:233], v[94:95]
	v_pk_fma_f32 v[64:65], v[234:235], v[92:93], v[64:65]
	v_pk_mul_f32 v[66:67], v[232:233], v[88:89]
	v_pk_fma_f32 v[66:67], v[234:235], v[90:91], v[66:67]
	ds_read_b128 v[232:235], v74 offset:41728
	v_add_f32_e32 v152, v64, v65
	v_add_f32_e32 v173, v66, v67
	s_waitcnt lgkmcnt(10)
	v_pk_mul_f32 v[60:61], v[94:95], v[126:127]
	v_pk_mul_f32 v[62:63], v[88:89], v[126:127]
	v_pk_fma_f32 v[60:61], v[92:93], v[128:129], v[60:61]
	v_pk_fma_f32 v[62:63], v[90:91], v[128:129], v[62:63]
	v_add_f32_e32 v60, v60, v61
	v_add_f32_e32 v62, v62, v63
	v_pk_mul_f32 v[94:95], v[94:95], v[122:123]
	v_pk_mul_f32 v[92:93], v[92:93], v[124:125]
	v_add_f32_dpp v60, v60, v60 quad_perm:[1,0,3,2] row_mask:0xf bank_mask:0xf bound_ctrl:1
	v_add_f32_dpp v62, v62, v62 quad_perm:[1,0,3,2] row_mask:0xf bank_mask:0xf bound_ctrl:1
	v_pk_mul_f32 v[88:89], v[88:89], v[122:123]
	v_add_f32_dpp v60, v60, v60 quad_perm:[2,3,0,1] row_mask:0xf bank_mask:0xf bound_ctrl:1
	v_add_f32_dpp v62, v62, v62 quad_perm:[2,3,0,1] row_mask:0xf bank_mask:0xf bound_ctrl:1
	v_pk_mul_f32 v[90:91], v[90:91], v[124:125]
	s_waitcnt lgkmcnt(8)
	v_add_f32_dpp v60, v60, v60 row_half_mirror row_mask:0xf bank_mask:0xf bound_ctrl:1
	v_add_f32_dpp v62, v62, v62 row_half_mirror row_mask:0xf bank_mask:0xf bound_ctrl:1
	v_pk_fma_f32 v[94:95], v[142:143], v[134:135], v[94:95] op_sel_hi:[0,1,1]
	v_add_f32_dpp v60, v60, v60 row_mirror row_mask:0xf bank_mask:0xf bound_ctrl:1
	v_add_f32_dpp v62, v62, v62 row_mirror row_mask:0xf bank_mask:0xf bound_ctrl:1
	v_pk_fma_f32 v[92:93], v[142:143], v[136:137], v[92:93] op_sel_hi:[0,1,1]
	ds_read_b128 v[126:129], v74 offset:42496
	ds_read_b128 v[122:125], v74 offset:42240
	ds_read_b128 v[134:137], v74 offset:43008
	ds_read_b32 v142, v75 offset:43520
	s_waitcnt lgkmcnt(11)
	v_pk_fma_f32 v[94:95], v[130:131], v[60:61], v[94:95] op_sel_hi:[1,0,1] neg_lo:[1,0,0] neg_hi:[1,0,0]
	v_pk_fma_f32 v[92:93], v[132:133], v[60:61], v[92:93] op_sel_hi:[1,0,1] neg_lo:[1,0,0] neg_hi:[1,0,0]
	v_pk_fma_f32 v[88:89], v[130:131], v[62:63], v[88:89] op_sel_hi:[1,0,1] neg_lo:[1,0,0] neg_hi:[1,0,0]
	v_pk_fma_f32 v[90:91], v[132:133], v[62:63], v[90:91] op_sel_hi:[1,0,1] neg_lo:[1,0,0] neg_hi:[1,0,0]
	ds_read_b128 v[130:133], v74 offset:42752
	s_waitcnt lgkmcnt(11)
; template <bool DUAL>
; __device__ __forceinline__ void rwkv_tile(const Params& p, int l, int tile, unsigned char* smem) {
;     ...
;       for (int i = 0; i < 32; ++i) {
;         const int inx = (i + 1) & 31;
;         const float4 nw4 = *(const float4*)(rp + inx * 384), nkk4 = *(const float4*)(rp + inx * 384 + 64), nkb4 = *(const float4*)(rp + inx * 384 + 128);
;         const float4 nkd4 = *(const float4*)(rp + inx * 384 + 192), nr4 = *(const float4*)(rp + inx * 384 + 256);
;         const float nv = vp[inx * 384];
;         v2f t = sA * (v2f){kk4.x, kk4.y};
;         t = sB * (v2f){kk4.z, kk4.w} + t;
;         float sa = t.x + t.y, ia = 0.f;
;         if (DUAL) {
;           v2f ti = iA * (v2f){kk4.x, kk4.y};
;           ti = iB * (v2f){kk4.z, kk4.w} + ti;
;           ia = ti.x + ti.y;
;           sa += dppf<0xB1>(sa); ia += dppf<0xB1>(ia);
;           sa += dppf<0x4E>(sa); ia += dppf<0x4E>(ia);
;           sa += dppf<0x141>(sa); ia += dppf<0x141>(ia);
;           sa += dppf<0x140>(sa); ia += dppf<0x140>(ia);
;         } else {
;           sa = sum16(sa);
;         }
;         v2f cA = sA * (v2f){w4.x, w4.y} + (v2f){kd4.x, kd4.y} * v;
;         v2f cB = sB * (v2f){w4.z, w4.w} + (v2f){kd4.z, kd4.w} * v;
;         sA = cA - (v2f){kb4.x, kb4.y} * sa;
;         sB = cB - (v2f){kb4.z, kb4.w} * sa;
;         v2f u = sA * (v2f){r4.x, r4.y};
;         u = sB * (v2f){r4.z, r4.w} + u;
;         float y = u.x + u.y, g = 0.f;
;         if (DUAL) {
;           iA = iA * (v2f){w4.x, w4.y} - (v2f){kb4.x, kb4.y} * ia;
;           iB = iB * (v2f){w4.z, w4.w} - (v2f){kb4.z, kb4.w} * ia;
;           v2f ui = iA * (v2f){r4.x, r4.y};
;           ui = iB * (v2f){r4.z, r4.w} + ui;
;           g = ui.x + ui.y;
;           y += dppf<0xB1>(y); g += dppf<0xB1>(g);
;           y += dppf<0x4E>(y); g += dppf<0x4E>(g);
;           y += dppf<0x141>(y); g += dppf<0x141>(g);
;           y += dppf<0x140>(y); g += dppf<0x140>(g);
	v_pk_mul_f32 v[64:65], v[138:139], v[94:95]
	v_pk_fma_f32 v[64:65], v[140:141], v[92:93], v[64:65]
	v_pk_mul_f32 v[66:67], v[138:139], v[88:89]
	v_pk_fma_f32 v[66:67], v[140:141], v[90:91], v[66:67]
	ds_read_b128 v[138:141], v74 offset:43264
	v_add_f32_e32 v153, v64, v65
	v_add_f32_e32 v174, v66, v67
	s_waitcnt lgkmcnt(10)
	v_pk_mul_f32 v[60:61], v[94:95], v[220:221]
	v_pk_mul_f32 v[62:63], v[88:89], v[220:221]
	v_pk_fma_f32 v[60:61], v[92:93], v[222:223], v[60:61]
	v_pk_fma_f32 v[62:63], v[90:91], v[222:223], v[62:63]
	v_add_f32_e32 v60, v60, v61
	v_add_f32_e32 v62, v62, v63
	v_pk_mul_f32 v[94:95], v[94:95], v[216:217]
	v_pk_mul_f32 v[92:93], v[92:93], v[218:219]
	v_add_f32_dpp v60, v60, v60 quad_perm:[1,0,3,2] row_mask:0xf bank_mask:0xf bound_ctrl:1
	v_add_f32_dpp v62, v62, v62 quad_perm:[1,0,3,2] row_mask:0xf bank_mask:0xf bound_ctrl:1
	v_pk_mul_f32 v[88:89], v[88:89], v[216:217]
	v_add_f32_dpp v60, v60, v60 quad_perm:[2,3,0,1] row_mask:0xf bank_mask:0xf bound_ctrl:1
	v_add_f32_dpp v62, v62, v62 quad_perm:[2,3,0,1] row_mask:0xf bank_mask:0xf bound_ctrl:1
	v_pk_mul_f32 v[90:91], v[90:91], v[218:219]
	s_waitcnt lgkmcnt(8)
	v_add_f32_dpp v60, v60, v60 row_half_mirror row_mask:0xf bank_mask:0xf bound_ctrl:1
	v_add_f32_dpp v62, v62, v62 row_half_mirror row_mask:0xf bank_mask:0xf bound_ctrl:1
	v_pk_fma_f32 v[94:95], v[236:237], v[228:229], v[94:95] op_sel_hi:[0,1,1]
	v_add_f32_dpp v60, v60, v60 row_mirror row_mask:0xf bank_mask:0xf bound_ctrl:1
	v_add_f32_dpp v62, v62, v62 row_mirror row_mask:0xf bank_mask:0xf bound_ctrl:1
	v_pk_fma_f32 v[92:93], v[236:237], v[230:231], v[92:93] op_sel_hi:[0,1,1]
	ds_read_b128 v[220:223], v74 offset:44032
	ds_read_b128 v[216:219], v74 offset:43776
	ds_read_b128 v[228:231], v74 offset:44544
	ds_read_b32 v236, v75 offset:45056
	s_waitcnt lgkmcnt(11)
	v_pk_fma_f32 v[94:95], v[224:225], v[60:61], v[94:95] op_sel_hi:[1,0,1] neg_lo:[1,0,0] neg_hi:[1,0,0]
	v_pk_fma_f32 v[92:93], v[226:227], v[60:61], v[92:93] op_sel_hi:[1,0,1] neg_lo:[1,0,0] neg_hi:[1,0,0]
	v_pk_fma_f32 v[88:89], v[224:225], v[62:63], v[88:89] op_sel_hi:[1,0,1] neg_lo:[1,0,0] neg_hi:[1,0,0]
	v_pk_fma_f32 v[90:91], v[226:227], v[62:63], v[90:91] op_sel_hi:[1,0,1] neg_lo:[1,0,0] neg_hi:[1,0,0]
	ds_read_b128 v[224:227], v74 offset:44288
	s_waitcnt lgkmcnt(11)
	v_pk_mul_f32 v[64:65], v[232:233], v[94:95]
	v_pk_fma_f32 v[64:65], v[234:235], v[92:93], v[64:65]
	v_pk_mul_f32 v[66:67], v[232:233], v[88:89]
	v_pk_fma_f32 v[66:67], v[234:235], v[90:91], v[66:67]
	ds_read_b128 v[232:235], v74 offset:44800
	v_add_f32_e32 v154, v64, v65
	v_add_f32_e32 v175, v66, v67
	s_waitcnt lgkmcnt(10)
	v_pk_mul_f32 v[60:61], v[94:95], v[126:127]
	v_pk_mul_f32 v[62:63], v[88:89], v[126:127]
	v_pk_fma_f32 v[60:61], v[92:93], v[128:129], v[60:61]
	v_pk_fma_f32 v[62:63], v[90:91], v[128:129], v[62:63]
	v_add_f32_e32 v60, v60, v61
	v_add_f32_e32 v62, v62, v63
	v_pk_mul_f32 v[94:95], v[94:95], v[122:123]
	v_pk_mul_f32 v[92:93], v[92:93], v[124:125]
	v_add_f32_dpp v60, v60, v60 quad_perm:[1,0,3,2] row_mask:0xf bank_mask:0xf bound_ctrl:1
	v_add_f32_dpp v62, v62, v62 quad_perm:[1,0,3,2] row_mask:0xf bank_mask:0xf bound_ctrl:1
	v_pk_mul_f32 v[88:89], v[88:89], v[122:123]
	v_add_f32_dpp v60, v60, v60 quad_perm:[2,3,0,1] row_mask:0xf bank_mask:0xf bound_ctrl:1
	v_add_f32_dpp v62, v62, v62 quad_perm:[2,3,0,1] row_mask:0xf bank_mask:0xf bound_ctrl:1
	v_pk_mul_f32 v[90:91], v[90:91], v[124:125]
	s_waitcnt lgkmcnt(8)
	v_add_f32_dpp v60, v60, v60 row_half_mirror row_mask:0xf bank_mask:0xf bound_ctrl:1
	v_add_f32_dpp v62, v62, v62 row_half_mirror row_mask:0xf bank_mask:0xf bound_ctrl:1
	v_pk_fma_f32 v[94:95], v[142:143], v[134:135], v[94:95] op_sel_hi:[0,1,1]
	v_add_f32_dpp v60, v60, v60 row_mirror row_mask:0xf bank_mask:0xf bound_ctrl:1
	v_add_f32_dpp v62, v62, v62 row_mirror row_mask:0xf bank_mask:0xf bound_ctrl:1
	v_pk_fma_f32 v[92:93], v[142:143], v[136:137], v[92:93] op_sel_hi:[0,1,1]
	ds_read_b128 v[126:129], v74 offset:45568
	ds_read_b128 v[122:125], v74 offset:45312
	ds_read_b128 v[134:137], v74 offset:46080
	ds_read_b32 v142, v75 offset:46592
	s_waitcnt lgkmcnt(11)
	v_pk_fma_f32 v[94:95], v[130:131], v[60:61], v[94:95] op_sel_hi:[1,0,1] neg_lo:[1,0,0] neg_hi:[1,0,0]
	v_pk_fma_f32 v[92:93], v[132:133], v[60:61], v[92:93] op_sel_hi:[1,0,1] neg_lo:[1,0,0] neg_hi:[1,0,0]
	v_pk_fma_f32 v[88:89], v[130:131], v[62:63], v[88:89] op_sel_hi:[1,0,1] neg_lo:[1,0,0] neg_hi:[1,0,0]
	v_pk_fma_f32 v[90:91], v[132:133], v[62:63], v[90:91] op_sel_hi:[1,0,1] neg_lo:[1,0,0] neg_hi:[1,0,0]
	ds_read_b128 v[130:133], v74 offset:45824
	s_waitcnt lgkmcnt(11)
	v_pk_mul_f32 v[64:65], v[138:139], v[94:95]
	v_pk_fma_f32 v[64:65], v[140:141], v[92:93], v[64:65]
	v_pk_mul_f32 v[66:67], v[138:139], v[88:89]
	v_pk_fma_f32 v[66:67], v[140:141], v[90:91], v[66:67]
	ds_read_b128 v[138:141], v74 offset:46336
	v_add_f32_e32 v155, v64, v65
	v_add_f32_e32 v176, v66, v67
	s_waitcnt lgkmcnt(10)
	v_pk_mul_f32 v[60:61], v[94:95], v[220:221]
	v_pk_mul_f32 v[62:63], v[88:89], v[220:221]
	v_pk_fma_f32 v[60:61], v[92:93], v[222:223], v[60:61]
	v_pk_fma_f32 v[62:63], v[90:91], v[222:223], v[62:63]
	v_add_f32_e32 v60, v60, v61
	v_add_f32_e32 v62, v62, v63
	v_pk_mul_f32 v[94:95], v[94:95], v[216:217]
	v_pk_mul_f32 v[92:93], v[92:93], v[218:219]
	v_add_f32_dpp v60, v60, v60 quad_perm:[1,0,3,2] row_mask:0xf bank_mask:0xf bound_ctrl:1
	v_add_f32_dpp v62, v62, v62 quad_perm:[1,0,3,2] row_mask:0xf bank_mask:0xf bound_ctrl:1
	v_pk_mul_f32 v[88:89], v[88:89], v[216:217]
	v_add_f32_dpp v60, v60, v60 quad_perm:[2,3,0,1] row_mask:0xf bank_mask:0xf bound_ctrl:1
	v_add_f32_dpp v62, v62, v62 quad_perm:[2,3,0,1] row_mask:0xf bank_mask:0xf bound_ctrl:1
	v_pk_mul_f32 v[90:91], v[90:91], v[218:219]
	s_waitcnt lgkmcnt(8)
; template <bool DUAL>
; __device__ __forceinline__ void rwkv_tile(const Params& p, int l, int tile, unsigned char* smem) {
;     ...
;         v2f t = sA * (v2f){kk4.x, kk4.y};
;         t = sB * (v2f){kk4.z, kk4.w} + t;
;         float sa = t.x + t.y, ia = 0.f;
;         if (DUAL) {
;           v2f ti = iA * (v2f){kk4.x, kk4.y};
;           ti = iB * (v2f){kk4.z, kk4.w} + ti;
;           ia = ti.x + ti.y;
;           sa += dppf<0xB1>(sa); ia += dppf<0xB1>(ia);
;           sa += dppf<0x4E>(sa); ia += dppf<0x4E>(ia);
;           sa += dppf<0x141>(sa); ia += dppf<0x141>(ia);
;           sa += dppf<0x140>(sa); ia += dppf<0x140>(ia);
;         } else {
;           sa = sum16(sa);
;         }
;         v2f cA = sA * (v2f){w4.x, w4.y} + (v2f){kd4.x, kd4.y} * v;
;         v2f cB = sB * (v2f){w4.z, w4.w} + (v2f){kd4.z, kd4.w} * v;
;         sA = cA - (v2f){kb4.x, kb4.y} * sa;
;         sB = cB - (v2f){kb4.z, kb4.w} * sa;
;         v2f u = sA * (v2f){r4.x, r4.y};
;         u = sB * (v2f){r4.z, r4.w} + u;
;         float y = u.x + u.y, g = 0.f;
;         if (DUAL) {
;           iA = iA * (v2f){w4.x, w4.y} - (v2f){kb4.x, kb4.y} * ia;
;           iB = iB * (v2f){w4.z, w4.w} - (v2f){kb4.z, kb4.w} * ia;
;           v2f ui = iA * (v2f){r4.x, r4.y};
;           ui = iB * (v2f){r4.z, r4.w} + ui;
;           g = ui.x + ui.y;
;           y += dppf<0xB1>(y); g += dppf<0xB1>(g);
;           y += dppf<0x4E>(y); g += dppf<0x4E>(g);
;           y += dppf<0x141>(y); g += dppf<0x141>(g);
;           y += dppf<0x140>(y); g += dppf<0x140>(g);
;           if (fr == (i & 15)) gkeep = g;
	v_add_f32_dpp v60, v60, v60 row_half_mirror row_mask:0xf bank_mask:0xf bound_ctrl:1
	v_add_f32_dpp v62, v62, v62 row_half_mirror row_mask:0xf bank_mask:0xf bound_ctrl:1
	v_pk_fma_f32 v[94:95], v[236:237], v[228:229], v[94:95] op_sel_hi:[0,1,1]
	v_add_f32_dpp v60, v60, v60 row_mirror row_mask:0xf bank_mask:0xf bound_ctrl:1
	v_add_f32_dpp v62, v62, v62 row_mirror row_mask:0xf bank_mask:0xf bound_ctrl:1
	v_pk_fma_f32 v[92:93], v[236:237], v[230:231], v[92:93] op_sel_hi:[0,1,1]
	ds_read_b128 v[220:223], v74 offset:47104
	ds_read_b128 v[216:219], v74 offset:46848
	ds_read_b128 v[228:231], v74 offset:47616
	ds_read_b32 v236, v75 offset:48128
	s_waitcnt lgkmcnt(11)
	v_pk_fma_f32 v[94:95], v[224:225], v[60:61], v[94:95] op_sel_hi:[1,0,1] neg_lo:[1,0,0] neg_hi:[1,0,0]
	v_pk_fma_f32 v[92:93], v[226:227], v[60:61], v[92:93] op_sel_hi:[1,0,1] neg_lo:[1,0,0] neg_hi:[1,0,0]
	v_pk_fma_f32 v[88:89], v[224:225], v[62:63], v[88:89] op_sel_hi:[1,0,1] neg_lo:[1,0,0] neg_hi:[1,0,0]
	v_pk_fma_f32 v[90:91], v[226:227], v[62:63], v[90:91] op_sel_hi:[1,0,1] neg_lo:[1,0,0] neg_hi:[1,0,0]
	ds_read_b128 v[224:227], v74 offset:47360
	s_waitcnt lgkmcnt(11)
	v_pk_mul_f32 v[64:65], v[232:233], v[94:95]
	v_pk_fma_f32 v[64:65], v[234:235], v[92:93], v[64:65]
	v_pk_mul_f32 v[66:67], v[232:233], v[88:89]
	v_pk_fma_f32 v[66:67], v[234:235], v[90:91], v[66:67]
	ds_read_b128 v[232:235], v74 offset:47872
	v_add_f32_e32 v156, v64, v65
	v_add_f32_e32 v177, v66, v67
	s_waitcnt lgkmcnt(10)
	v_pk_mul_f32 v[60:61], v[94:95], v[126:127]
	v_pk_mul_f32 v[62:63], v[88:89], v[126:127]
	v_pk_fma_f32 v[60:61], v[92:93], v[128:129], v[60:61]
	v_pk_fma_f32 v[62:63], v[90:91], v[128:129], v[62:63]
	v_add_f32_e32 v60, v60, v61
	v_add_f32_e32 v62, v62, v63
	v_pk_mul_f32 v[94:95], v[94:95], v[122:123]
	v_pk_mul_f32 v[92:93], v[92:93], v[124:125]
	v_add_f32_dpp v60, v60, v60 quad_perm:[1,0,3,2] row_mask:0xf bank_mask:0xf bound_ctrl:1
	v_add_f32_dpp v62, v62, v62 quad_perm:[1,0,3,2] row_mask:0xf bank_mask:0xf bound_ctrl:1
	v_pk_mul_f32 v[88:89], v[88:89], v[122:123]
	v_add_f32_dpp v60, v60, v60 quad_perm:[2,3,0,1] row_mask:0xf bank_mask:0xf bound_ctrl:1
	v_add_f32_dpp v62, v62, v62 quad_perm:[2,3,0,1] row_mask:0xf bank_mask:0xf bound_ctrl:1
	v_pk_mul_f32 v[90:91], v[90:91], v[124:125]
	s_waitcnt lgkmcnt(8)
	v_add_f32_dpp v60, v60, v60 row_half_mirror row_mask:0xf bank_mask:0xf bound_ctrl:1
	v_add_f32_dpp v62, v62, v62 row_half_mirror row_mask:0xf bank_mask:0xf bound_ctrl:1
	v_pk_fma_f32 v[94:95], v[142:143], v[134:135], v[94:95] op_sel_hi:[0,1,1]
	v_add_f32_dpp v60, v60, v60 row_mirror row_mask:0xf bank_mask:0xf bound_ctrl:1
	v_add_f32_dpp v62, v62, v62 row_mirror row_mask:0xf bank_mask:0xf bound_ctrl:1
	v_pk_fma_f32 v[92:93], v[142:143], v[136:137], v[92:93] op_sel_hi:[0,1,1]
	ds_read_b128 v[126:129], v74 offset:48640
	ds_read_b128 v[122:125], v74 offset:48384
	ds_read_b128 v[134:137], v74 offset:49152
	ds_read_b32 v142, v75 offset:49664
	s_waitcnt lgkmcnt(11)
	v_pk_fma_f32 v[94:95], v[130:131], v[60:61], v[94:95] op_sel_hi:[1,0,1] neg_lo:[1,0,0] neg_hi:[1,0,0]
	v_pk_fma_f32 v[92:93], v[132:133], v[60:61], v[92:93] op_sel_hi:[1,0,1] neg_lo:[1,0,0] neg_hi:[1,0,0]
	v_pk_fma_f32 v[88:89], v[130:131], v[62:63], v[88:89] op_sel_hi:[1,0,1] neg_lo:[1,0,0] neg_hi:[1,0,0]
	v_pk_fma_f32 v[90:91], v[132:133], v[62:63], v[90:91] op_sel_hi:[1,0,1] neg_lo:[1,0,0] neg_hi:[1,0,0]
	ds_read_b128 v[130:133], v74 offset:48896
	s_waitcnt lgkmcnt(11)
	v_pk_mul_f32 v[64:65], v[138:139], v[94:95]
	v_pk_fma_f32 v[64:65], v[140:141], v[92:93], v[64:65]
	v_pk_mul_f32 v[66:67], v[138:139], v[88:89]
	v_pk_fma_f32 v[66:67], v[140:141], v[90:91], v[66:67]
	ds_read_b128 v[138:141], v74 offset:49408
	v_add_f32_e32 v157, v64, v65
	v_add_f32_e32 v178, v66, v67
	s_waitcnt lgkmcnt(10)
	v_pk_mul_f32 v[60:61], v[94:95], v[220:221]
	v_pk_mul_f32 v[62:63], v[88:89], v[220:221]
	v_pk_fma_f32 v[60:61], v[92:93], v[222:223], v[60:61]
	v_pk_fma_f32 v[62:63], v[90:91], v[222:223], v[62:63]
	v_add_f32_e32 v60, v60, v61
	v_add_f32_e32 v62, v62, v63
	v_pk_mul_f32 v[94:95], v[94:95], v[216:217]
	v_pk_mul_f32 v[92:93], v[92:93], v[218:219]
	v_add_f32_dpp v60, v60, v60 quad_perm:[1,0,3,2] row_mask:0xf bank_mask:0xf bound_ctrl:1
	v_add_f32_dpp v62, v62, v62 quad_perm:[1,0,3,2] row_mask:0xf bank_mask:0xf bound_ctrl:1
	v_pk_mul_f32 v[88:89], v[88:89], v[216:217]
	v_add_f32_dpp v60, v60, v60 quad_perm:[2,3,0,1] row_mask:0xf bank_mask:0xf bound_ctrl:1
	v_add_f32_dpp v62, v62, v62 quad_perm:[2,3,0,1] row_mask:0xf bank_mask:0xf bound_ctrl:1
	v_pk_mul_f32 v[90:91], v[90:91], v[218:219]
	s_waitcnt lgkmcnt(8)
	v_add_f32_dpp v60, v60, v60 row_half_mirror row_mask:0xf bank_mask:0xf bound_ctrl:1
	v_add_f32_dpp v62, v62, v62 row_half_mirror row_mask:0xf bank_mask:0xf bound_ctrl:1
	v_pk_fma_f32 v[94:95], v[236:237], v[228:229], v[94:95] op_sel_hi:[0,1,1]
	v_add_f32_dpp v60, v60, v60 row_mirror row_mask:0xf bank_mask:0xf bound_ctrl:1
	v_add_f32_dpp v62, v62, v62 row_mirror row_mask:0xf bank_mask:0xf bound_ctrl:1
	v_pk_fma_f32 v[92:93], v[236:237], v[230:231], v[92:93] op_sel_hi:[0,1,1]
	ds_read_b128 v[220:223], v69 offset:25600
	ds_read_b128 v[216:219], v69 offset:25344
	ds_read_b128 v[228:231], v69 offset:26112
	ds_read_b32 v236, v70 offset:26624
	s_waitcnt lgkmcnt(11)
	v_pk_fma_f32 v[94:95], v[224:225], v[60:61], v[94:95] op_sel_hi:[1,0,1] neg_lo:[1,0,0] neg_hi:[1,0,0]
	v_pk_fma_f32 v[92:93], v[226:227], v[60:61], v[92:93] op_sel_hi:[1,0,1] neg_lo:[1,0,0] neg_hi:[1,0,0]
	v_pk_fma_f32 v[88:89], v[224:225], v[62:63], v[88:89] op_sel_hi:[1,0,1] neg_lo:[1,0,0] neg_hi:[1,0,0]
	v_pk_fma_f32 v[90:91], v[226:227], v[62:63], v[90:91] op_sel_hi:[1,0,1] neg_lo:[1,0,0] neg_hi:[1,0,0]
	ds_read_b128 v[224:227], v69 offset:25856
	s_waitcnt lgkmcnt(11)
; template <bool DUAL>
; __device__ __forceinline__ void rwkv_tile(const Params& p, int l, int tile, unsigned char* smem) {
;     ...
;         v2f cA = sA * (v2f){w4.x, w4.y} + (v2f){kd4.x, kd4.y} * v;
;         v2f cB = sB * (v2f){w4.z, w4.w} + (v2f){kd4.z, kd4.w} * v;
;         sA = cA - (v2f){kb4.x, kb4.y} * sa;
;         sB = cB - (v2f){kb4.z, kb4.w} * sa;
;         v2f u = sA * (v2f){r4.x, r4.y};
;         u = sB * (v2f){r4.z, r4.w} + u;
;         float y = u.x + u.y, g = 0.f;
;         if (DUAL) {
;           iA = iA * (v2f){w4.x, w4.y} - (v2f){kb4.x, kb4.y} * ia;
;           iB = iB * (v2f){w4.z, w4.w} - (v2f){kb4.z, kb4.w} * ia;
;           v2f ui = iA * (v2f){r4.x, r4.y};
;           ui = iB * (v2f){r4.z, r4.w} + ui;
;           g = ui.x + ui.y;
	v_pk_mul_f32 v[64:65], v[232:233], v[94:95]
	v_pk_fma_f32 v[64:65], v[234:235], v[92:93], v[64:65]
	v_pk_mul_f32 v[66:67], v[232:233], v[88:89]
	v_pk_fma_f32 v[66:67], v[234:235], v[90:91], v[66:67]
	ds_read_b128 v[232:235], v69 offset:26368
	v_add_f32_e32 v158, v64, v65
	v_add_f32_e32 v179, v66, v67
	s_waitcnt lgkmcnt(10)
	v_pk_mul_f32 v[60:61], v[94:95], v[126:127]
	v_pk_mul_f32 v[62:63], v[88:89], v[126:127]
	v_pk_fma_f32 v[60:61], v[92:93], v[128:129], v[60:61]
	v_pk_fma_f32 v[62:63], v[90:91], v[128:129], v[62:63]
	v_add_f32_e32 v60, v60, v61
	v_add_f32_e32 v62, v62, v63
	v_pk_mul_f32 v[94:95], v[94:95], v[122:123]
	v_pk_mul_f32 v[92:93], v[92:93], v[124:125]
	v_add_f32_dpp v60, v60, v60 quad_perm:[1,0,3,2] row_mask:0xf bank_mask:0xf bound_ctrl:1
	v_add_f32_dpp v62, v62, v62 quad_perm:[1,0,3,2] row_mask:0xf bank_mask:0xf bound_ctrl:1
	v_pk_mul_f32 v[88:89], v[88:89], v[122:123]
	v_add_f32_dpp v60, v60, v60 quad_perm:[2,3,0,1] row_mask:0xf bank_mask:0xf bound_ctrl:1
	v_add_f32_dpp v62, v62, v62 quad_perm:[2,3,0,1] row_mask:0xf bank_mask:0xf bound_ctrl:1
	v_pk_mul_f32 v[90:91], v[90:91], v[124:125]
	s_waitcnt lgkmcnt(8)
	v_add_f32_dpp v60, v60, v60 row_half_mirror row_mask:0xf bank_mask:0xf bound_ctrl:1
	v_add_f32_dpp v62, v62, v62 row_half_mirror row_mask:0xf bank_mask:0xf bound_ctrl:1
	v_pk_fma_f32 v[94:95], v[142:143], v[134:135], v[94:95] op_sel_hi:[0,1,1]
	v_add_f32_dpp v60, v60, v60 row_mirror row_mask:0xf bank_mask:0xf bound_ctrl:1
	v_add_f32_dpp v62, v62, v62 row_mirror row_mask:0xf bank_mask:0xf bound_ctrl:1
	v_pk_fma_f32 v[92:93], v[142:143], v[136:137], v[92:93] op_sel_hi:[0,1,1]
	ds_read_b128 v[126:129], v69 offset:27136
	ds_read_b128 v[122:125], v69 offset:26880
	ds_read_b128 v[134:137], v69 offset:27648
	ds_read_b32 v142, v70 offset:28160
	s_waitcnt lgkmcnt(11)
	v_pk_fma_f32 v[94:95], v[130:131], v[60:61], v[94:95] op_sel_hi:[1,0,1] neg_lo:[1,0,0] neg_hi:[1,0,0]
	v_pk_fma_f32 v[92:93], v[132:133], v[60:61], v[92:93] op_sel_hi:[1,0,1] neg_lo:[1,0,0] neg_hi:[1,0,0]
	v_pk_fma_f32 v[88:89], v[130:131], v[62:63], v[88:89] op_sel_hi:[1,0,1] neg_lo:[1,0,0] neg_hi:[1,0,0]
	v_pk_fma_f32 v[90:91], v[132:133], v[62:63], v[90:91] op_sel_hi:[1,0,1] neg_lo:[1,0,0] neg_hi:[1,0,0]
	ds_read_b128 v[130:133], v69 offset:27392
	s_waitcnt lgkmcnt(11)
; __device__ __forceinline__ bf16_t f2bf(float f) { return (bf16_t)(pack2(f, 0.f) & 0xffffu); }
; template <bool DUAL>
; __device__ __forceinline__ void rwkv_tile(const Params& p, int l, int tile, unsigned char* smem) {
;     ...
;         v2f cA = sA * (v2f){w4.x, w4.y} + (v2f){kd4.x, kd4.y} * v;
;         v2f cB = sB * (v2f){w4.z, w4.w} + (v2f){kd4.z, kd4.w} * v;
;         sA = cA - (v2f){kb4.x, kb4.y} * sa;
;         sB = cB - (v2f){kb4.z, kb4.w} * sa;
;         v2f u = sA * (v2f){r4.x, r4.y};
;         u = sB * (v2f){r4.z, r4.w} + u;
;         float y = u.x + u.y, g = 0.f;
;         if (DUAL) {
;           iA = iA * (v2f){w4.x, w4.y} - (v2f){kb4.x, kb4.y} * ia;
;           iB = iB * (v2f){w4.z, w4.w} - (v2f){kb4.z, kb4.w} * ia;
;           v2f ui = iA * (v2f){r4.x, r4.y};
;           ui = iB * (v2f){r4.z, r4.w} + ui;
;           g = ui.x + ui.y;
;           y += dppf<0xB1>(y); g += dppf<0xB1>(g);
;           y += dppf<0x4E>(y); g += dppf<0x4E>(g);
;           y += dppf<0x141>(y); g += dppf<0x141>(g);
;           y += dppf<0x140>(y); g += dppf<0x140>(g);
;           if (fr == (i & 15)) gkeep = g;
;         } else {
;           y = sum16(y);
;         }
;         if (fr == (i & 15)) ykeep = y;
;         if ((i & 15) == 15) {
;           const int ii = (i & 16) + fr;
;           const int ri = (d == 0) ? ii + 1 : 32 - ii;
;           const int pi = plo - 1 + ri;
;           p.yR[((size_t)d * TOK + rowbase + pi) * 256 + h * 64 + row] = f2bf(ykeep);
;           if (DUAL) p.GID[((size_t)(d * 4 + b) * NSEG1 + (cix - CSPLIT) * 32 + ii) * 256 + h * 64 + row] = f2bf(gkeep);
;         }
	v_pk_mul_f32 v[64:65], v[138:139], v[94:95]
	v_pk_fma_f32 v[64:65], v[140:141], v[92:93], v[64:65]
	v_pk_mul_f32 v[66:67], v[138:139], v[88:89]
	v_pk_fma_f32 v[66:67], v[140:141], v[90:91], v[66:67]
	ds_read_b128 v[138:141], v69 offset:27904
	v_add_f32_e32 v159, v64, v65
	v_add_f32_e32 v180, v66, v67
	v_add_f32_dpp v144, v144, v144 row_shl:8 row_mask:0xf bank_mask:0x3
	v_add_f32_dpp v144, v152, v152 row_shr:8 row_mask:0xf bank_mask:0xc
	v_add_f32_dpp v145, v145, v145 row_shl:8 row_mask:0xf bank_mask:0x3
	v_add_f32_dpp v145, v153, v153 row_shr:8 row_mask:0xf bank_mask:0xc
	v_add_f32_dpp v146, v146, v146 row_shl:8 row_mask:0xf bank_mask:0x3
	v_add_f32_dpp v146, v154, v154 row_shr:8 row_mask:0xf bank_mask:0xc
	v_add_f32_dpp v147, v147, v147 row_shl:8 row_mask:0xf bank_mask:0x3
	v_add_f32_dpp v147, v155, v155 row_shr:8 row_mask:0xf bank_mask:0xc
	v_add_f32_dpp v148, v148, v148 row_shl:8 row_mask:0xf bank_mask:0x3
	v_add_f32_dpp v148, v156, v156 row_shr:8 row_mask:0xf bank_mask:0xc
	v_add_f32_dpp v149, v149, v149 row_shl:8 row_mask:0xf bank_mask:0x3
	v_add_f32_dpp v149, v157, v157 row_shr:8 row_mask:0xf bank_mask:0xc
	v_add_f32_dpp v150, v150, v150 row_shl:8 row_mask:0xf bank_mask:0x3
	v_add_f32_dpp v150, v158, v158 row_shr:8 row_mask:0xf bank_mask:0xc
	v_add_f32_dpp v151, v151, v151 row_shl:8 row_mask:0xf bank_mask:0x3
	v_add_f32_dpp v151, v159, v159 row_shr:8 row_mask:0xf bank_mask:0xc
	v_add_f32_dpp v144, v144, v144 row_shl:4 row_mask:0xf bank_mask:0x5
	v_add_f32_dpp v144, v148, v148 row_shr:4 row_mask:0xf bank_mask:0xa
	v_add_f32_dpp v145, v145, v145 row_shl:4 row_mask:0xf bank_mask:0x5
	v_add_f32_dpp v145, v149, v149 row_shr:4 row_mask:0xf bank_mask:0xa
	v_add_f32_dpp v146, v146, v146 row_shl:4 row_mask:0xf bank_mask:0x5
	v_add_f32_dpp v146, v150, v150 row_shr:4 row_mask:0xf bank_mask:0xa
	v_add_f32_dpp v147, v147, v147 row_shl:4 row_mask:0xf bank_mask:0x5
	v_add_f32_dpp v147, v151, v151 row_shr:4 row_mask:0xf bank_mask:0xa
	v_cndmask_b32_e32 v160, v144, v146, vcc
	v_cndmask_b32_e32 v161, v146, v144, vcc
	v_cndmask_b32_e32 v163, v147, v145, vcc
	v_cndmask_b32_e32 v162, v145, v147, vcc
	v_add_f32_dpp v160, v161, v160 quad_perm:[2,3,0,1] row_mask:0xf bank_mask:0xf
	v_add_f32_dpp v162, v163, v162 quad_perm:[2,3,0,1] row_mask:0xf bank_mask:0xf
	v_cndmask_b32_e64 v181, v160, v162, s[58:59]
	v_cndmask_b32_e64 v182, v162, v160, s[58:59]
	v_add_u32_e32 v74, 0x6000, v74
	v_add_u32_e32 v75, 0x6000, v75
	v_add_f32_dpp v72, v182, v181 quad_perm:[1,0,3,2] row_mask:0xf bank_mask:0xf
	v_add_f32_dpp v165, v165, v165 row_shl:8 row_mask:0xf bank_mask:0x3
	v_add_f32_dpp v165, v173, v173 row_shr:8 row_mask:0xf bank_mask:0xc
	v_add_f32_dpp v166, v166, v166 row_shl:8 row_mask:0xf bank_mask:0x3
	v_add_f32_dpp v166, v174, v174 row_shr:8 row_mask:0xf bank_mask:0xc
	v_add_f32_dpp v167, v167, v167 row_shl:8 row_mask:0xf bank_mask:0x3
	v_add_f32_dpp v167, v175, v175 row_shr:8 row_mask:0xf bank_mask:0xc
	v_add_f32_dpp v168, v168, v168 row_shl:8 row_mask:0xf bank_mask:0x3
	v_add_f32_dpp v168, v176, v176 row_shr:8 row_mask:0xf bank_mask:0xc
	v_add_f32_dpp v169, v169, v169 row_shl:8 row_mask:0xf bank_mask:0x3
	v_add_f32_dpp v169, v177, v177 row_shr:8 row_mask:0xf bank_mask:0xc
	v_add_f32_dpp v170, v170, v170 row_shl:8 row_mask:0xf bank_mask:0x3
	v_add_f32_dpp v170, v178, v178 row_shr:8 row_mask:0xf bank_mask:0xc
	v_add_f32_dpp v171, v171, v171 row_shl:8 row_mask:0xf bank_mask:0x3
	v_add_f32_dpp v171, v179, v179 row_shr:8 row_mask:0xf bank_mask:0xc
	v_add_f32_dpp v172, v172, v172 row_shl:8 row_mask:0xf bank_mask:0x3
	v_add_f32_dpp v172, v180, v180 row_shr:8 row_mask:0xf bank_mask:0xc
	v_add_f32_dpp v165, v165, v165 row_shl:4 row_mask:0xf bank_mask:0x5
	v_add_f32_dpp v165, v169, v169 row_shr:4 row_mask:0xf bank_mask:0xa
	v_add_f32_dpp v166, v166, v166 row_shl:4 row_mask:0xf bank_mask:0x5
	v_add_f32_dpp v166, v170, v170 row_shr:4 row_mask:0xf bank_mask:0xa
	v_add_f32_dpp v167, v167, v167 row_shl:4 row_mask:0xf bank_mask:0x5
	v_add_f32_dpp v167, v171, v171 row_shr:4 row_mask:0xf bank_mask:0xa
	v_add_f32_dpp v168, v168, v168 row_shl:4 row_mask:0xf bank_mask:0x5
	v_add_f32_dpp v168, v172, v172 row_shr:4 row_mask:0xf bank_mask:0xa
	v_cndmask_b32_e32 v160, v165, v167, vcc
	v_cndmask_b32_e32 v161, v167, v165, vcc
	v_cndmask_b32_e32 v163, v168, v166, vcc
	v_cndmask_b32_e32 v162, v166, v168, vcc
	v_add_f32_dpp v160, v161, v160 quad_perm:[2,3,0,1] row_mask:0xf bank_mask:0xf
	v_add_f32_dpp v162, v163, v162 quad_perm:[2,3,0,1] row_mask:0xf bank_mask:0xf
	v_cndmask_b32_e64 v181, v160, v162, s[58:59]
	v_cndmask_b32_e64 v182, v162, v160, s[58:59]
	v_mov_b32_e32 v69, v102
	v_mov_b32_e32 v70, v103
	v_add_f32_dpp v73, v182, v181 quad_perm:[1,0,3,2] row_mask:0xf bank_mask:0xf
	v_mov_b32_e32 v79, v68
	v_add_u32_e32 v77, 1, v79
	v_sub_u32_e32 v76, 32, v79
	v_cndmask_b32_e64 v76, v76, v77, s[36:37]
	v_add_u32_e32 v76, s28, v76
	v_ashrrev_i32_e32 v77, 31, v76
	v_lshl_add_u64 v[76:77], s[20:21], 0, v[76:77]
	v_lshlrev_b64 v[76:77], 9, v[76:77]
	v_cvt_pk_bf16_f32 v78, v72, v72
	v_lshl_add_u64 v[76:77], v[84:85], 0, v[76:77]
	global_store_short v[76:77], v78, off
	v_or_b32_e32 v76, s53, v79
	v_mov_b32_e32 v77, s54
	v_cvt_pk_bf16_f32 v79, v73, v73
	v_lshlrev_b64 v[76:77], 9, v[76:77]
	v_lshl_add_u64 v[76:77], v[86:87], 0, v[76:77]
	global_store_short v[76:77], v79, off
	v_add_u32_e32 v68, 16, v68
	s_add_i32 s55, s55, 1
	s_cmp_lg_u32 s55, 2
	s_cbranch_scc1 .Lrw_du_loop
	s_branch .LBB0_1436

; __device__ __forceinline__ bf16_t f2bf(float f) { return (bf16_t)(pack2(f, 0.f) & 0xffffu); }
; template <bool DUAL>
; __device__ __forceinline__ void rwkv_tile(const Params& p, int l, int tile, unsigned char* smem) {
;     ...
; #pragma unroll 2
;       for (int i = 0; i < 32; ++i) {
;         const int inx = (i + 1) & 31;
;         const float4 nw4 = *(const float4*)(rp + inx * 384), nkk4 = *(const float4*)(rp + inx * 384 + 64), nkb4 = *(const float4*)(rp + inx * 384 + 128);
;         const float4 nkd4 = *(const float4*)(rp + inx * 384 + 192), nr4 = *(const float4*)(rp + inx * 384 + 256);
;         const float nv = vp[inx * 384];
;         v2f t = sA * (v2f){kk4.x, kk4.y};
;         t = sB * (v2f){kk4.z, kk4.w} + t;
;         float sa = t.x + t.y, ia = 0.f;
;         if (DUAL) {
;           v2f ti = iA * (v2f){kk4.x, kk4.y};
;           ti = iB * (v2f){kk4.z, kk4.w} + ti;
;           ia = ti.x + ti.y;
;           sa += dppf<0xB1>(sa); ia += dppf<0xB1>(ia);
;           sa += dppf<0x4E>(sa); ia += dppf<0x4E>(ia);
;           sa += dppf<0x141>(sa); ia += dppf<0x141>(ia);
;           sa += dppf<0x140>(sa); ia += dppf<0x140>(ia);
;         } else {
;           sa = sum16(sa);
;         }
;         v2f cA = sA * (v2f){w4.x, w4.y} + (v2f){kd4.x, kd4.y} * v;
;         v2f cB = sB * (v2f){w4.z, w4.w} + (v2f){kd4.z, kd4.w} * v;
;         sA = cA - (v2f){kb4.x, kb4.y} * sa;
;         sB = cB - (v2f){kb4.z, kb4.w} * sa;
;         v2f u = sA * (v2f){r4.x, r4.y};
;         u = sB * (v2f){r4.z, r4.w} + u;
;     ...
;           y = sum16(y);
;         }
;         if (fr == (i & 15)) ykeep = y;
;         if ((i & 15) == 15) {
;           const int ii = (i & 16) + fr;
;           const int ri = (d == 0) ? ii + 1 : 32 - ii;
;           const int pi = plo - 1 + ri;
;           p.yR[((size_t)d * TOK + rowbase + pi) * 256 + h * 64 + row] = f2bf(ykeep);
;           if (DUAL) p.GID[((size_t)(d * 4 + b) * NSEG1 + (cix - CSPLIT) * 32 + ii) * 256 + h * 64 + row] = f2bf(gkeep);
;         }
;         w4 = nw4; kk4 = nkk4; kb4 = nkb4; kd4 = nkd4; r4 = nr4; v = nv;
.Lrw_nd_loop:
	s_waitcnt lgkmcnt(10)
	v_pk_mul_f32 v[64:65], v[60:61], v[220:221]
	v_pk_fma_f32 v[64:65], v[62:63], v[222:223], v[64:65]
	v_add_f32_e32 v64, v64, v65
	v_pk_mul_f32 v[60:61], v[60:61], v[216:217]
	v_pk_mul_f32 v[62:63], v[62:63], v[218:219]
	v_add_f32_dpp v64, v64, v64 quad_perm:[1,0,3,2] row_mask:0xf bank_mask:0xf bound_ctrl:1
	s_waitcnt lgkmcnt(8)
	v_pk_fma_f32 v[60:61], v[236:237], v[228:229], v[60:61] op_sel_hi:[0,1,1]
	v_pk_fma_f32 v[62:63], v[236:237], v[230:231], v[62:63] op_sel_hi:[0,1,1]
	v_add_f32_dpp v64, v64, v64 quad_perm:[2,3,0,1] row_mask:0xf bank_mask:0xf bound_ctrl:1
	ds_read_b128 v[220:223], v72 offset:28672
	ds_read_b128 v[216:219], v72 offset:28416
	v_add_f32_dpp v64, v64, v64 row_half_mirror row_mask:0xf bank_mask:0xf bound_ctrl:1
	ds_read_b128 v[228:231], v72 offset:29184
	ds_read_b32 v236, v73 offset:29696
	v_add_f32_dpp v64, v64, v64 row_mirror row_mask:0xf bank_mask:0xf bound_ctrl:1
	s_waitcnt lgkmcnt(11)
	v_pk_fma_f32 v[60:61], v[224:225], v[64:65], v[60:61] op_sel_hi:[1,0,1] neg_lo:[1,0,0] neg_hi:[1,0,0]
	v_pk_fma_f32 v[62:63], v[226:227], v[64:65], v[62:63] op_sel_hi:[1,0,1] neg_lo:[1,0,0] neg_hi:[1,0,0]
	ds_read_b128 v[224:227], v72 offset:28928
	s_waitcnt lgkmcnt(11)
	v_pk_mul_f32 v[66:67], v[232:233], v[60:61]
	v_pk_fma_f32 v[66:67], v[234:235], v[62:63], v[66:67]
	ds_read_b128 v[232:235], v72 offset:29440
	v_add_f32_e32 v140, v66, v67
	s_waitcnt lgkmcnt(10)
	v_pk_mul_f32 v[64:65], v[60:61], v[122:123]
	v_pk_fma_f32 v[64:65], v[62:63], v[124:125], v[64:65]
	v_add_f32_e32 v64, v64, v65
	v_pk_mul_f32 v[60:61], v[60:61], v[118:119]
	v_pk_mul_f32 v[62:63], v[62:63], v[120:121]
	v_add_f32_dpp v64, v64, v64 quad_perm:[1,0,3,2] row_mask:0xf bank_mask:0xf bound_ctrl:1
	s_waitcnt lgkmcnt(8)
	v_pk_fma_f32 v[60:61], v[138:139], v[130:131], v[60:61] op_sel_hi:[0,1,1]
	v_pk_fma_f32 v[62:63], v[138:139], v[132:133], v[62:63] op_sel_hi:[0,1,1]
	v_add_f32_dpp v64, v64, v64 quad_perm:[2,3,0,1] row_mask:0xf bank_mask:0xf bound_ctrl:1
	ds_read_b128 v[122:125], v72 offset:30208
	ds_read_b128 v[118:121], v72 offset:29952
	v_add_f32_dpp v64, v64, v64 row_half_mirror row_mask:0xf bank_mask:0xf bound_ctrl:1
	ds_read_b128 v[130:133], v72 offset:30720
	ds_read_b32 v138, v73 offset:31232
	v_add_f32_dpp v64, v64, v64 row_mirror row_mask:0xf bank_mask:0xf bound_ctrl:1
	s_waitcnt lgkmcnt(11)
	v_pk_fma_f32 v[60:61], v[126:127], v[64:65], v[60:61] op_sel_hi:[1,0,1] neg_lo:[1,0,0] neg_hi:[1,0,0]
	v_pk_fma_f32 v[62:63], v[128:129], v[64:65], v[62:63] op_sel_hi:[1,0,1] neg_lo:[1,0,0] neg_hi:[1,0,0]
	ds_read_b128 v[126:129], v72 offset:30464
	s_waitcnt lgkmcnt(11)
	v_pk_mul_f32 v[66:67], v[134:135], v[60:61]
	v_pk_fma_f32 v[66:67], v[136:137], v[62:63], v[66:67]
	ds_read_b128 v[134:137], v72 offset:30976
	v_add_f32_e32 v141, v66, v67
	s_waitcnt lgkmcnt(10)
	v_pk_mul_f32 v[64:65], v[60:61], v[220:221]
	v_pk_fma_f32 v[64:65], v[62:63], v[222:223], v[64:65]
	v_add_f32_e32 v64, v64, v65
	v_pk_mul_f32 v[60:61], v[60:61], v[216:217]
	v_pk_mul_f32 v[62:63], v[62:63], v[218:219]
	v_add_f32_dpp v64, v64, v64 quad_perm:[1,0,3,2] row_mask:0xf bank_mask:0xf bound_ctrl:1
	s_waitcnt lgkmcnt(8)
	v_pk_fma_f32 v[60:61], v[236:237], v[228:229], v[60:61] op_sel_hi:[0,1,1]
	v_pk_fma_f32 v[62:63], v[236:237], v[230:231], v[62:63] op_sel_hi:[0,1,1]
	v_add_f32_dpp v64, v64, v64 quad_perm:[2,3,0,1] row_mask:0xf bank_mask:0xf bound_ctrl:1
	ds_read_b128 v[220:223], v72 offset:31744
	ds_read_b128 v[216:219], v72 offset:31488
	v_add_f32_dpp v64, v64, v64 row_half_mirror row_mask:0xf bank_mask:0xf bound_ctrl:1
	ds_read_b128 v[228:231], v72 offset:32256
	ds_read_b32 v236, v73 offset:32768
	v_add_f32_dpp v64, v64, v64 row_mirror row_mask:0xf bank_mask:0xf bound_ctrl:1
	s_waitcnt lgkmcnt(11)
	v_pk_fma_f32 v[60:61], v[224:225], v[64:65], v[60:61] op_sel_hi:[1,0,1] neg_lo:[1,0,0] neg_hi:[1,0,0]
	v_pk_fma_f32 v[62:63], v[226:227], v[64:65], v[62:63] op_sel_hi:[1,0,1] neg_lo:[1,0,0] neg_hi:[1,0,0]
	ds_read_b128 v[224:227], v72 offset:32000
	s_waitcnt lgkmcnt(11)
	v_pk_mul_f32 v[66:67], v[232:233], v[60:61]
	v_pk_fma_f32 v[66:67], v[234:235], v[62:63], v[66:67]
	ds_read_b128 v[232:235], v72 offset:32512
	v_add_f32_e32 v142, v66, v67
	s_waitcnt lgkmcnt(10)
	v_pk_mul_f32 v[64:65], v[60:61], v[122:123]
	v_pk_fma_f32 v[64:65], v[62:63], v[124:125], v[64:65]
	v_add_f32_e32 v64, v64, v65
	v_pk_mul_f32 v[60:61], v[60:61], v[118:119]
	v_pk_mul_f32 v[62:63], v[62:63], v[120:121]
	v_add_f32_dpp v64, v64, v64 quad_perm:[1,0,3,2] row_mask:0xf bank_mask:0xf bound_ctrl:1
	s_waitcnt lgkmcnt(8)
	v_pk_fma_f32 v[60:61], v[138:139], v[130:131], v[60:61] op_sel_hi:[0,1,1]
	v_pk_fma_f32 v[62:63], v[138:139], v[132:133], v[62:63] op_sel_hi:[0,1,1]
	v_add_f32_dpp v64, v64, v64 quad_perm:[2,3,0,1] row_mask:0xf bank_mask:0xf bound_ctrl:1
	ds_read_b128 v[122:125], v72 offset:33280
	ds_read_b128 v[118:121], v72 offset:33024
	v_add_f32_dpp v64, v64, v64 row_half_mirror row_mask:0xf bank_mask:0xf bound_ctrl:1
	ds_read_b128 v[130:133], v72 offset:33792
	ds_read_b32 v138, v73 offset:34304
	v_add_f32_dpp v64, v64, v64 row_mirror row_mask:0xf bank_mask:0xf bound_ctrl:1
	s_waitcnt lgkmcnt(11)
	v_pk_fma_f32 v[60:61], v[126:127], v[64:65], v[60:61] op_sel_hi:[1,0,1] neg_lo:[1,0,0] neg_hi:[1,0,0]
	v_pk_fma_f32 v[62:63], v[128:129], v[64:65], v[62:63] op_sel_hi:[1,0,1] neg_lo:[1,0,0] neg_hi:[1,0,0]
	ds_read_b128 v[126:129], v72 offset:33536
	s_waitcnt lgkmcnt(11)
	v_pk_mul_f32 v[66:67], v[134:135], v[60:61]
	v_pk_fma_f32 v[66:67], v[136:137], v[62:63], v[66:67]
	ds_read_b128 v[134:137], v72 offset:34048
	v_add_f32_e32 v143, v66, v67
	s_waitcnt lgkmcnt(10)
; __device__ __forceinline__ bf16_t f2bf(float f) { return (bf16_t)(pack2(f, 0.f) & 0xffffu); }
; template <bool DUAL>
; __device__ __forceinline__ void rwkv_tile(const Params& p, int l, int tile, unsigned char* smem) {
;     ...
; #pragma unroll 2
;       for (int i = 0; i < 32; ++i) {
;         const int inx = (i + 1) & 31;
;         const float4 nw4 = *(const float4*)(rp + inx * 384), nkk4 = *(const float4*)(rp + inx * 384 + 64), nkb4 = *(const float4*)(rp + inx * 384 + 128);
;         const float4 nkd4 = *(const float4*)(rp + inx * 384 + 192), nr4 = *(const float4*)(rp + inx * 384 + 256);
;         const float nv = vp[inx * 384];
;         v2f t = sA * (v2f){kk4.x, kk4.y};
;         t = sB * (v2f){kk4.z, kk4.w} + t;
;         float sa = t.x + t.y, ia = 0.f;
;         if (DUAL) {
;           v2f ti = iA * (v2f){kk4.x, kk4.y};
;           ti = iB * (v2f){kk4.z, kk4.w} + ti;
;           ia = ti.x + ti.y;
;           sa += dppf<0xB1>(sa); ia += dppf<0xB1>(ia);
;           sa += dppf<0x4E>(sa); ia += dppf<0x4E>(ia);
;           sa += dppf<0x141>(sa); ia += dppf<0x141>(ia);
;           sa += dppf<0x140>(sa); ia += dppf<0x140>(ia);
;         } else {
;           sa = sum16(sa);
;         }
;         v2f cA = sA * (v2f){w4.x, w4.y} + (v2f){kd4.x, kd4.y} * v;
;         v2f cB = sB * (v2f){w4.z, w4.w} + (v2f){kd4.z, kd4.w} * v;
;         sA = cA - (v2f){kb4.x, kb4.y} * sa;
;         sB = cB - (v2f){kb4.z, kb4.w} * sa;
;         v2f u = sA * (v2f){r4.x, r4.y};
;         u = sB * (v2f){r4.z, r4.w} + u;
;     ...
;           y = sum16(y);
;         }
;         if (fr == (i & 15)) ykeep = y;
;         if ((i & 15) == 15) {
;           const int ii = (i & 16) + fr;
;           const int ri = (d == 0) ? ii + 1 : 32 - ii;
;           const int pi = plo - 1 + ri;
;           p.yR[((size_t)d * TOK + rowbase + pi) * 256 + h * 64 + row] = f2bf(ykeep);
;           if (DUAL) p.GID[((size_t)(d * 4 + b) * NSEG1 + (cix - CSPLIT) * 32 + ii) * 256 + h * 64 + row] = f2bf(gkeep);
;         }
;         w4 = nw4; kk4 = nkk4; kb4 = nkb4; kd4 = nkd4; r4 = nr4; v = nv;
	v_pk_mul_f32 v[64:65], v[60:61], v[220:221]
	v_pk_fma_f32 v[64:65], v[62:63], v[222:223], v[64:65]
	v_add_f32_e32 v64, v64, v65
	v_pk_mul_f32 v[60:61], v[60:61], v[216:217]
	v_pk_mul_f32 v[62:63], v[62:63], v[218:219]
	v_add_f32_dpp v64, v64, v64 quad_perm:[1,0,3,2] row_mask:0xf bank_mask:0xf bound_ctrl:1
	s_waitcnt lgkmcnt(8)
	v_pk_fma_f32 v[60:61], v[236:237], v[228:229], v[60:61] op_sel_hi:[0,1,1]
	v_pk_fma_f32 v[62:63], v[236:237], v[230:231], v[62:63] op_sel_hi:[0,1,1]
	v_add_f32_dpp v64, v64, v64 quad_perm:[2,3,0,1] row_mask:0xf bank_mask:0xf bound_ctrl:1
	ds_read_b128 v[220:223], v72 offset:34816
	ds_read_b128 v[216:219], v72 offset:34560
	v_add_f32_dpp v64, v64, v64 row_half_mirror row_mask:0xf bank_mask:0xf bound_ctrl:1
	ds_read_b128 v[228:231], v72 offset:35328
	ds_read_b32 v236, v73 offset:35840
	v_add_f32_dpp v64, v64, v64 row_mirror row_mask:0xf bank_mask:0xf bound_ctrl:1
	s_waitcnt lgkmcnt(11)
	v_pk_fma_f32 v[60:61], v[224:225], v[64:65], v[60:61] op_sel_hi:[1,0,1] neg_lo:[1,0,0] neg_hi:[1,0,0]
	v_pk_fma_f32 v[62:63], v[226:227], v[64:65], v[62:63] op_sel_hi:[1,0,1] neg_lo:[1,0,0] neg_hi:[1,0,0]
	ds_read_b128 v[224:227], v72 offset:35072
	s_waitcnt lgkmcnt(11)
	v_pk_mul_f32 v[66:67], v[232:233], v[60:61]
	v_pk_fma_f32 v[66:67], v[234:235], v[62:63], v[66:67]
	ds_read_b128 v[232:235], v72 offset:35584
	v_add_f32_e32 v144, v66, v67
	s_waitcnt lgkmcnt(10)
	v_pk_mul_f32 v[64:65], v[60:61], v[122:123]
	v_pk_fma_f32 v[64:65], v[62:63], v[124:125], v[64:65]
	v_add_f32_e32 v64, v64, v65
	v_pk_mul_f32 v[60:61], v[60:61], v[118:119]
	v_pk_mul_f32 v[62:63], v[62:63], v[120:121]
	v_add_f32_dpp v64, v64, v64 quad_perm:[1,0,3,2] row_mask:0xf bank_mask:0xf bound_ctrl:1
	s_waitcnt lgkmcnt(8)
	v_pk_fma_f32 v[60:61], v[138:139], v[130:131], v[60:61] op_sel_hi:[0,1,1]
	v_pk_fma_f32 v[62:63], v[138:139], v[132:133], v[62:63] op_sel_hi:[0,1,1]
	v_add_f32_dpp v64, v64, v64 quad_perm:[2,3,0,1] row_mask:0xf bank_mask:0xf bound_ctrl:1
	ds_read_b128 v[122:125], v72 offset:36352
	ds_read_b128 v[118:121], v72 offset:36096
	v_add_f32_dpp v64, v64, v64 row_half_mirror row_mask:0xf bank_mask:0xf bound_ctrl:1
	ds_read_b128 v[130:133], v72 offset:36864
	ds_read_b32 v138, v73 offset:37376
	v_add_f32_dpp v64, v64, v64 row_mirror row_mask:0xf bank_mask:0xf bound_ctrl:1
	s_waitcnt lgkmcnt(11)
	v_pk_fma_f32 v[60:61], v[126:127], v[64:65], v[60:61] op_sel_hi:[1,0,1] neg_lo:[1,0,0] neg_hi:[1,0,0]
	v_pk_fma_f32 v[62:63], v[128:129], v[64:65], v[62:63] op_sel_hi:[1,0,1] neg_lo:[1,0,0] neg_hi:[1,0,0]
	ds_read_b128 v[126:129], v72 offset:36608
	s_waitcnt lgkmcnt(11)
	v_pk_mul_f32 v[66:67], v[134:135], v[60:61]
	v_pk_fma_f32 v[66:67], v[136:137], v[62:63], v[66:67]
	ds_read_b128 v[134:137], v72 offset:37120
	v_add_f32_e32 v145, v66, v67
	s_waitcnt lgkmcnt(10)
	v_pk_mul_f32 v[64:65], v[60:61], v[220:221]
	v_pk_fma_f32 v[64:65], v[62:63], v[222:223], v[64:65]
	v_add_f32_e32 v64, v64, v65
	v_pk_mul_f32 v[60:61], v[60:61], v[216:217]
	v_pk_mul_f32 v[62:63], v[62:63], v[218:219]
	v_add_f32_dpp v64, v64, v64 quad_perm:[1,0,3,2] row_mask:0xf bank_mask:0xf bound_ctrl:1
	s_waitcnt lgkmcnt(8)
	v_pk_fma_f32 v[60:61], v[236:237], v[228:229], v[60:61] op_sel_hi:[0,1,1]
	v_pk_fma_f32 v[62:63], v[236:237], v[230:231], v[62:63] op_sel_hi:[0,1,1]
	v_add_f32_dpp v64, v64, v64 quad_perm:[2,3,0,1] row_mask:0xf bank_mask:0xf bound_ctrl:1
	ds_read_b128 v[220:223], v72 offset:37888
	ds_read_b128 v[216:219], v72 offset:37632
	v_add_f32_dpp v64, v64, v64 row_half_mirror row_mask:0xf bank_mask:0xf bound_ctrl:1
	ds_read_b128 v[228:231], v72 offset:38400
	ds_read_b32 v236, v73 offset:38912
	v_add_f32_dpp v64, v64, v64 row_mirror row_mask:0xf bank_mask:0xf bound_ctrl:1
	s_waitcnt lgkmcnt(11)
	v_pk_fma_f32 v[60:61], v[224:225], v[64:65], v[60:61] op_sel_hi:[1,0,1] neg_lo:[1,0,0] neg_hi:[1,0,0]
	v_pk_fma_f32 v[62:63], v[226:227], v[64:65], v[62:63] op_sel_hi:[1,0,1] neg_lo:[1,0,0] neg_hi:[1,0,0]
	ds_read_b128 v[224:227], v72 offset:38144
	s_waitcnt lgkmcnt(11)
	v_pk_mul_f32 v[66:67], v[232:233], v[60:61]
	v_pk_fma_f32 v[66:67], v[234:235], v[62:63], v[66:67]
	ds_read_b128 v[232:235], v72 offset:38656
	v_add_f32_e32 v146, v66, v67
	s_waitcnt lgkmcnt(10)
	v_pk_mul_f32 v[64:65], v[60:61], v[122:123]
	v_pk_fma_f32 v[64:65], v[62:63], v[124:125], v[64:65]
	v_add_f32_e32 v64, v64, v65
	v_pk_mul_f32 v[60:61], v[60:61], v[118:119]
	v_pk_mul_f32 v[62:63], v[62:63], v[120:121]
	v_add_f32_dpp v64, v64, v64 quad_perm:[1,0,3,2] row_mask:0xf bank_mask:0xf bound_ctrl:1
	s_waitcnt lgkmcnt(8)
	v_pk_fma_f32 v[60:61], v[138:139], v[130:131], v[60:61] op_sel_hi:[0,1,1]
	v_pk_fma_f32 v[62:63], v[138:139], v[132:133], v[62:63] op_sel_hi:[0,1,1]
	v_add_f32_dpp v64, v64, v64 quad_perm:[2,3,0,1] row_mask:0xf bank_mask:0xf bound_ctrl:1
	ds_read_b128 v[122:125], v72 offset:39424
	ds_read_b128 v[118:121], v72 offset:39168
	v_add_f32_dpp v64, v64, v64 row_half_mirror row_mask:0xf bank_mask:0xf bound_ctrl:1
	ds_read_b128 v[130:133], v72 offset:39936
	ds_read_b32 v138, v73 offset:40448
	v_add_f32_dpp v64, v64, v64 row_mirror row_mask:0xf bank_mask:0xf bound_ctrl:1
	s_waitcnt lgkmcnt(11)
	v_pk_fma_f32 v[60:61], v[126:127], v[64:65], v[60:61] op_sel_hi:[1,0,1] neg_lo:[1,0,0] neg_hi:[1,0,0]
	v_pk_fma_f32 v[62:63], v[128:129], v[64:65], v[62:63] op_sel_hi:[1,0,1] neg_lo:[1,0,0] neg_hi:[1,0,0]
	ds_read_b128 v[126:129], v72 offset:39680
	s_waitcnt lgkmcnt(11)
	v_pk_mul_f32 v[66:67], v[134:135], v[60:61]
	v_pk_fma_f32 v[66:67], v[136:137], v[62:63], v[66:67]
	ds_read_b128 v[134:137], v72 offset:40192
	v_add_f32_e32 v147, v66, v67
	s_waitcnt lgkmcnt(10)
; __device__ __forceinline__ bf16_t f2bf(float f) { return (bf16_t)(pack2(f, 0.f) & 0xffffu); }
; template <bool DUAL>
; __device__ __forceinline__ void rwkv_tile(const Params& p, int l, int tile, unsigned char* smem) {
;     ...
; #pragma unroll 2
;       for (int i = 0; i < 32; ++i) {
;         const int inx = (i + 1) & 31;
;         const float4 nw4 = *(const float4*)(rp + inx * 384), nkk4 = *(const float4*)(rp + inx * 384 + 64), nkb4 = *(const float4*)(rp + inx * 384 + 128);
;         const float4 nkd4 = *(const float4*)(rp + inx * 384 + 192), nr4 = *(const float4*)(rp + inx * 384 + 256);
;         const float nv = vp[inx * 384];
;         v2f t = sA * (v2f){kk4.x, kk4.y};
;         t = sB * (v2f){kk4.z, kk4.w} + t;
;         float sa = t.x + t.y, ia = 0.f;
;         if (DUAL) {
;           v2f ti = iA * (v2f){kk4.x, kk4.y};
;           ti = iB * (v2f){kk4.z, kk4.w} + ti;
;           ia = ti.x + ti.y;
;           sa += dppf<0xB1>(sa); ia += dppf<0xB1>(ia);
;           sa += dppf<0x4E>(sa); ia += dppf<0x4E>(ia);
;           sa += dppf<0x141>(sa); ia += dppf<0x141>(ia);
;           sa += dppf<0x140>(sa); ia += dppf<0x140>(ia);
;         } else {
;           sa = sum16(sa);
;         }
;         v2f cA = sA * (v2f){w4.x, w4.y} + (v2f){kd4.x, kd4.y} * v;
;         v2f cB = sB * (v2f){w4.z, w4.w} + (v2f){kd4.z, kd4.w} * v;
;         sA = cA - (v2f){kb4.x, kb4.y} * sa;
;         sB = cB - (v2f){kb4.z, kb4.w} * sa;
;         v2f u = sA * (v2f){r4.x, r4.y};
;         u = sB * (v2f){r4.z, r4.w} + u;
;     ...
;           y = sum16(y);
;         }
;         if (fr == (i & 15)) ykeep = y;
;         if ((i & 15) == 15) {
;           const int ii = (i & 16) + fr;
;           const int ri = (d == 0) ? ii + 1 : 32 - ii;
;           const int pi = plo - 1 + ri;
;           p.yR[((size_t)d * TOK + rowbase + pi) * 256 + h * 64 + row] = f2bf(ykeep);
;           if (DUAL) p.GID[((size_t)(d * 4 + b) * NSEG1 + (cix - CSPLIT) * 32 + ii) * 256 + h * 64 + row] = f2bf(gkeep);
;         }
;         w4 = nw4; kk4 = nkk4; kb4 = nkb4; kd4 = nkd4; r4 = nr4; v = nv;
	v_pk_mul_f32 v[64:65], v[60:61], v[220:221]
	v_pk_fma_f32 v[64:65], v[62:63], v[222:223], v[64:65]
	v_add_f32_e32 v64, v64, v65
	v_pk_mul_f32 v[60:61], v[60:61], v[216:217]
	v_pk_mul_f32 v[62:63], v[62:63], v[218:219]
	v_add_f32_dpp v64, v64, v64 quad_perm:[1,0,3,2] row_mask:0xf bank_mask:0xf bound_ctrl:1
	s_waitcnt lgkmcnt(8)
	v_pk_fma_f32 v[60:61], v[236:237], v[228:229], v[60:61] op_sel_hi:[0,1,1]
	v_pk_fma_f32 v[62:63], v[236:237], v[230:231], v[62:63] op_sel_hi:[0,1,1]
	v_add_f32_dpp v64, v64, v64 quad_perm:[2,3,0,1] row_mask:0xf bank_mask:0xf bound_ctrl:1
	ds_read_b128 v[220:223], v72 offset:40960
	ds_read_b128 v[216:219], v72 offset:40704
	v_add_f32_dpp v64, v64, v64 row_half_mirror row_mask:0xf bank_mask:0xf bound_ctrl:1
	ds_read_b128 v[228:231], v72 offset:41472
	ds_read_b32 v236, v73 offset:41984
	v_add_f32_dpp v64, v64, v64 row_mirror row_mask:0xf bank_mask:0xf bound_ctrl:1
	s_waitcnt lgkmcnt(11)
	v_pk_fma_f32 v[60:61], v[224:225], v[64:65], v[60:61] op_sel_hi:[1,0,1] neg_lo:[1,0,0] neg_hi:[1,0,0]
	v_pk_fma_f32 v[62:63], v[226:227], v[64:65], v[62:63] op_sel_hi:[1,0,1] neg_lo:[1,0,0] neg_hi:[1,0,0]
	ds_read_b128 v[224:227], v72 offset:41216
	s_waitcnt lgkmcnt(11)
	v_pk_mul_f32 v[66:67], v[232:233], v[60:61]
	v_pk_fma_f32 v[66:67], v[234:235], v[62:63], v[66:67]
	ds_read_b128 v[232:235], v72 offset:41728
	v_add_f32_e32 v148, v66, v67
	s_waitcnt lgkmcnt(10)
	v_pk_mul_f32 v[64:65], v[60:61], v[122:123]
	v_pk_fma_f32 v[64:65], v[62:63], v[124:125], v[64:65]
	v_add_f32_e32 v64, v64, v65
	v_pk_mul_f32 v[60:61], v[60:61], v[118:119]
	v_pk_mul_f32 v[62:63], v[62:63], v[120:121]
	v_add_f32_dpp v64, v64, v64 quad_perm:[1,0,3,2] row_mask:0xf bank_mask:0xf bound_ctrl:1
	s_waitcnt lgkmcnt(8)
	v_pk_fma_f32 v[60:61], v[138:139], v[130:131], v[60:61] op_sel_hi:[0,1,1]
	v_pk_fma_f32 v[62:63], v[138:139], v[132:133], v[62:63] op_sel_hi:[0,1,1]
	v_add_f32_dpp v64, v64, v64 quad_perm:[2,3,0,1] row_mask:0xf bank_mask:0xf bound_ctrl:1
	ds_read_b128 v[122:125], v72 offset:42496
	ds_read_b128 v[118:121], v72 offset:42240
	v_add_f32_dpp v64, v64, v64 row_half_mirror row_mask:0xf bank_mask:0xf bound_ctrl:1
	ds_read_b128 v[130:133], v72 offset:43008
	ds_read_b32 v138, v73 offset:43520
	v_add_f32_dpp v64, v64, v64 row_mirror row_mask:0xf bank_mask:0xf bound_ctrl:1
	s_waitcnt lgkmcnt(11)
	v_pk_fma_f32 v[60:61], v[126:127], v[64:65], v[60:61] op_sel_hi:[1,0,1] neg_lo:[1,0,0] neg_hi:[1,0,0]
	v_pk_fma_f32 v[62:63], v[128:129], v[64:65], v[62:63] op_sel_hi:[1,0,1] neg_lo:[1,0,0] neg_hi:[1,0,0]
	ds_read_b128 v[126:129], v72 offset:42752
	s_waitcnt lgkmcnt(11)
	v_pk_mul_f32 v[66:67], v[134:135], v[60:61]
	v_pk_fma_f32 v[66:67], v[136:137], v[62:63], v[66:67]
	ds_read_b128 v[134:137], v72 offset:43264
	v_add_f32_e32 v149, v66, v67
	s_waitcnt lgkmcnt(10)
	v_pk_mul_f32 v[64:65], v[60:61], v[220:221]
	v_pk_fma_f32 v[64:65], v[62:63], v[222:223], v[64:65]
	v_add_f32_e32 v64, v64, v65
	v_pk_mul_f32 v[60:61], v[60:61], v[216:217]
	v_pk_mul_f32 v[62:63], v[62:63], v[218:219]
	v_add_f32_dpp v64, v64, v64 quad_perm:[1,0,3,2] row_mask:0xf bank_mask:0xf bound_ctrl:1
	s_waitcnt lgkmcnt(8)
	v_pk_fma_f32 v[60:61], v[236:237], v[228:229], v[60:61] op_sel_hi:[0,1,1]
	v_pk_fma_f32 v[62:63], v[236:237], v[230:231], v[62:63] op_sel_hi:[0,1,1]
	v_add_f32_dpp v64, v64, v64 quad_perm:[2,3,0,1] row_mask:0xf bank_mask:0xf bound_ctrl:1
	ds_read_b128 v[220:223], v72 offset:44032
	ds_read_b128 v[216:219], v72 offset:43776
	v_add_f32_dpp v64, v64, v64 row_half_mirror row_mask:0xf bank_mask:0xf bound_ctrl:1
	ds_read_b128 v[228:231], v72 offset:44544
	ds_read_b32 v236, v73 offset:45056
	v_add_f32_dpp v64, v64, v64 row_mirror row_mask:0xf bank_mask:0xf bound_ctrl:1
	s_waitcnt lgkmcnt(11)
	v_pk_fma_f32 v[60:61], v[224:225], v[64:65], v[60:61] op_sel_hi:[1,0,1] neg_lo:[1,0,0] neg_hi:[1,0,0]
	v_pk_fma_f32 v[62:63], v[226:227], v[64:65], v[62:63] op_sel_hi:[1,0,1] neg_lo:[1,0,0] neg_hi:[1,0,0]
	ds_read_b128 v[224:227], v72 offset:44288
	s_waitcnt lgkmcnt(11)
	v_pk_mul_f32 v[66:67], v[232:233], v[60:61]
	v_pk_fma_f32 v[66:67], v[234:235], v[62:63], v[66:67]
	ds_read_b128 v[232:235], v72 offset:44800
	v_add_f32_e32 v150, v66, v67
	s_waitcnt lgkmcnt(10)
	v_pk_mul_f32 v[64:65], v[60:61], v[122:123]
	v_pk_fma_f32 v[64:65], v[62:63], v[124:125], v[64:65]
	v_add_f32_e32 v64, v64, v65
	v_pk_mul_f32 v[60:61], v[60:61], v[118:119]
	v_pk_mul_f32 v[62:63], v[62:63], v[120:121]
	v_add_f32_dpp v64, v64, v64 quad_perm:[1,0,3,2] row_mask:0xf bank_mask:0xf bound_ctrl:1
	s_waitcnt lgkmcnt(8)
	v_pk_fma_f32 v[60:61], v[138:139], v[130:131], v[60:61] op_sel_hi:[0,1,1]
	v_pk_fma_f32 v[62:63], v[138:139], v[132:133], v[62:63] op_sel_hi:[0,1,1]
	v_add_f32_dpp v64, v64, v64 quad_perm:[2,3,0,1] row_mask:0xf bank_mask:0xf bound_ctrl:1
	ds_read_b128 v[122:125], v72 offset:45568
	ds_read_b128 v[118:121], v72 offset:45312
	v_add_f32_dpp v64, v64, v64 row_half_mirror row_mask:0xf bank_mask:0xf bound_ctrl:1
	ds_read_b128 v[130:133], v72 offset:46080
	ds_read_b32 v138, v73 offset:46592
	v_add_f32_dpp v64, v64, v64 row_mirror row_mask:0xf bank_mask:0xf bound_ctrl:1
	s_waitcnt lgkmcnt(11)
	v_pk_fma_f32 v[60:61], v[126:127], v[64:65], v[60:61] op_sel_hi:[1,0,1] neg_lo:[1,0,0] neg_hi:[1,0,0]
	v_pk_fma_f32 v[62:63], v[128:129], v[64:65], v[62:63] op_sel_hi:[1,0,1] neg_lo:[1,0,0] neg_hi:[1,0,0]
	ds_read_b128 v[126:129], v72 offset:45824
	s_waitcnt lgkmcnt(11)
	v_pk_mul_f32 v[66:67], v[134:135], v[60:61]
	v_pk_fma_f32 v[66:67], v[136:137], v[62:63], v[66:67]
	ds_read_b128 v[134:137], v72 offset:46336
	v_add_f32_e32 v151, v66, v67
	s_waitcnt lgkmcnt(10)
; __device__ __forceinline__ bf16_t f2bf(float f) { return (bf16_t)(pack2(f, 0.f) & 0xffffu); }
; template <bool DUAL>
; __device__ __forceinline__ void rwkv_tile(const Params& p, int l, int tile, unsigned char* smem) {
;     ...
; #pragma unroll 2
;       for (int i = 0; i < 32; ++i) {
;         const int inx = (i + 1) & 31;
;         const float4 nw4 = *(const float4*)(rp + inx * 384), nkk4 = *(const float4*)(rp + inx * 384 + 64), nkb4 = *(const float4*)(rp + inx * 384 + 128);
;         const float4 nkd4 = *(const float4*)(rp + inx * 384 + 192), nr4 = *(const float4*)(rp + inx * 384 + 256);
;         const float nv = vp[inx * 384];
;         v2f t = sA * (v2f){kk4.x, kk4.y};
;         t = sB * (v2f){kk4.z, kk4.w} + t;
;         float sa = t.x + t.y, ia = 0.f;
;         if (DUAL) {
;           v2f ti = iA * (v2f){kk4.x, kk4.y};
;           ti = iB * (v2f){kk4.z, kk4.w} + ti;
;           ia = ti.x + ti.y;
;           sa += dppf<0xB1>(sa); ia += dppf<0xB1>(ia);
;           sa += dppf<0x4E>(sa); ia += dppf<0x4E>(ia);
;           sa += dppf<0x141>(sa); ia += dppf<0x141>(ia);
;           sa += dppf<0x140>(sa); ia += dppf<0x140>(ia);
;         } else {
;           sa = sum16(sa);
;         }
;         v2f cA = sA * (v2f){w4.x, w4.y} + (v2f){kd4.x, kd4.y} * v;
;         v2f cB = sB * (v2f){w4.z, w4.w} + (v2f){kd4.z, kd4.w} * v;
;         sA = cA - (v2f){kb4.x, kb4.y} * sa;
;         sB = cB - (v2f){kb4.z, kb4.w} * sa;
;         v2f u = sA * (v2f){r4.x, r4.y};
;         u = sB * (v2f){r4.z, r4.w} + u;
;     ...
;           y = sum16(y);
;         }
;         if (fr == (i & 15)) ykeep = y;
;         if ((i & 15) == 15) {
;           const int ii = (i & 16) + fr;
;           const int ri = (d == 0) ? ii + 1 : 32 - ii;
;           const int pi = plo - 1 + ri;
;           p.yR[((size_t)d * TOK + rowbase + pi) * 256 + h * 64 + row] = f2bf(ykeep);
;           if (DUAL) p.GID[((size_t)(d * 4 + b) * NSEG1 + (cix - CSPLIT) * 32 + ii) * 256 + h * 64 + row] = f2bf(gkeep);
;         }
;         w4 = nw4; kk4 = nkk4; kb4 = nkb4; kd4 = nkd4; r4 = nr4; v = nv;
	v_pk_mul_f32 v[64:65], v[60:61], v[220:221]
	v_pk_fma_f32 v[64:65], v[62:63], v[222:223], v[64:65]
	v_add_f32_e32 v64, v64, v65
	v_pk_mul_f32 v[60:61], v[60:61], v[216:217]
	v_pk_mul_f32 v[62:63], v[62:63], v[218:219]
	v_add_f32_dpp v64, v64, v64 quad_perm:[1,0,3,2] row_mask:0xf bank_mask:0xf bound_ctrl:1
	s_waitcnt lgkmcnt(8)
	v_pk_fma_f32 v[60:61], v[236:237], v[228:229], v[60:61] op_sel_hi:[0,1,1]
	v_pk_fma_f32 v[62:63], v[236:237], v[230:231], v[62:63] op_sel_hi:[0,1,1]
	v_add_f32_dpp v64, v64, v64 quad_perm:[2,3,0,1] row_mask:0xf bank_mask:0xf bound_ctrl:1
	ds_read_b128 v[220:223], v72 offset:47104
	ds_read_b128 v[216:219], v72 offset:46848
	v_add_f32_dpp v64, v64, v64 row_half_mirror row_mask:0xf bank_mask:0xf bound_ctrl:1
	ds_read_b128 v[228:231], v72 offset:47616
	ds_read_b32 v236, v73 offset:48128
	v_add_f32_dpp v64, v64, v64 row_mirror row_mask:0xf bank_mask:0xf bound_ctrl:1
	s_waitcnt lgkmcnt(11)
	v_pk_fma_f32 v[60:61], v[224:225], v[64:65], v[60:61] op_sel_hi:[1,0,1] neg_lo:[1,0,0] neg_hi:[1,0,0]
	v_pk_fma_f32 v[62:63], v[226:227], v[64:65], v[62:63] op_sel_hi:[1,0,1] neg_lo:[1,0,0] neg_hi:[1,0,0]
	ds_read_b128 v[224:227], v72 offset:47360
	s_waitcnt lgkmcnt(11)
	v_pk_mul_f32 v[66:67], v[232:233], v[60:61]
	v_pk_fma_f32 v[66:67], v[234:235], v[62:63], v[66:67]
	ds_read_b128 v[232:235], v72 offset:47872
	v_add_f32_e32 v152, v66, v67
	s_waitcnt lgkmcnt(10)
	v_pk_mul_f32 v[64:65], v[60:61], v[122:123]
	v_pk_fma_f32 v[64:65], v[62:63], v[124:125], v[64:65]
	v_add_f32_e32 v64, v64, v65
	v_pk_mul_f32 v[60:61], v[60:61], v[118:119]
	v_pk_mul_f32 v[62:63], v[62:63], v[120:121]
	v_add_f32_dpp v64, v64, v64 quad_perm:[1,0,3,2] row_mask:0xf bank_mask:0xf bound_ctrl:1
	s_waitcnt lgkmcnt(8)
	v_pk_fma_f32 v[60:61], v[138:139], v[130:131], v[60:61] op_sel_hi:[0,1,1]
	v_pk_fma_f32 v[62:63], v[138:139], v[132:133], v[62:63] op_sel_hi:[0,1,1]
	v_add_f32_dpp v64, v64, v64 quad_perm:[2,3,0,1] row_mask:0xf bank_mask:0xf bound_ctrl:1
	ds_read_b128 v[122:125], v72 offset:48640
	ds_read_b128 v[118:121], v72 offset:48384
	v_add_f32_dpp v64, v64, v64 row_half_mirror row_mask:0xf bank_mask:0xf bound_ctrl:1
	ds_read_b128 v[130:133], v72 offset:49152
	ds_read_b32 v138, v73 offset:49664
	v_add_f32_dpp v64, v64, v64 row_mirror row_mask:0xf bank_mask:0xf bound_ctrl:1
	s_waitcnt lgkmcnt(11)
	v_pk_fma_f32 v[60:61], v[126:127], v[64:65], v[60:61] op_sel_hi:[1,0,1] neg_lo:[1,0,0] neg_hi:[1,0,0]
	v_pk_fma_f32 v[62:63], v[128:129], v[64:65], v[62:63] op_sel_hi:[1,0,1] neg_lo:[1,0,0] neg_hi:[1,0,0]
	ds_read_b128 v[126:129], v72 offset:48896
	s_waitcnt lgkmcnt(11)
	v_pk_mul_f32 v[66:67], v[134:135], v[60:61]
	v_pk_fma_f32 v[66:67], v[136:137], v[62:63], v[66:67]
	ds_read_b128 v[134:137], v72 offset:49408
	v_add_f32_e32 v153, v66, v67
	s_waitcnt lgkmcnt(10)
	v_pk_mul_f32 v[64:65], v[60:61], v[220:221]
	v_pk_fma_f32 v[64:65], v[62:63], v[222:223], v[64:65]
	v_add_f32_e32 v64, v64, v65
	v_pk_mul_f32 v[60:61], v[60:61], v[216:217]
	v_pk_mul_f32 v[62:63], v[62:63], v[218:219]
	v_add_f32_dpp v64, v64, v64 quad_perm:[1,0,3,2] row_mask:0xf bank_mask:0xf bound_ctrl:1
	s_waitcnt lgkmcnt(8)
	v_pk_fma_f32 v[60:61], v[236:237], v[228:229], v[60:61] op_sel_hi:[0,1,1]
	v_pk_fma_f32 v[62:63], v[236:237], v[230:231], v[62:63] op_sel_hi:[0,1,1]
	v_add_f32_dpp v64, v64, v64 quad_perm:[2,3,0,1] row_mask:0xf bank_mask:0xf bound_ctrl:1
	ds_read_b128 v[220:223], v68 offset:25600
	ds_read_b128 v[216:219], v68 offset:25344
	v_add_f32_dpp v64, v64, v64 row_half_mirror row_mask:0xf bank_mask:0xf bound_ctrl:1
	ds_read_b128 v[228:231], v68 offset:26112
	ds_read_b32 v236, v69 offset:26624
	v_add_f32_dpp v64, v64, v64 row_mirror row_mask:0xf bank_mask:0xf bound_ctrl:1
	s_waitcnt lgkmcnt(11)
	v_pk_fma_f32 v[60:61], v[224:225], v[64:65], v[60:61] op_sel_hi:[1,0,1] neg_lo:[1,0,0] neg_hi:[1,0,0]
	v_pk_fma_f32 v[62:63], v[226:227], v[64:65], v[62:63] op_sel_hi:[1,0,1] neg_lo:[1,0,0] neg_hi:[1,0,0]
	ds_read_b128 v[224:227], v68 offset:25856
	s_waitcnt lgkmcnt(11)
	v_pk_mul_f32 v[66:67], v[232:233], v[60:61]
	v_pk_fma_f32 v[66:67], v[234:235], v[62:63], v[66:67]
	ds_read_b128 v[232:235], v68 offset:26368
	v_add_f32_e32 v154, v66, v67
	s_waitcnt lgkmcnt(10)
; template <bool DUAL>
; __device__ __forceinline__ void rwkv_tile(const Params& p, int l, int tile, unsigned char* smem) {
;     ...
; #pragma unroll 2
;       for (int i = 0; i < 32; ++i) {
;         const int inx = (i + 1) & 31;
;         const float4 nw4 = *(const float4*)(rp + inx * 384), nkk4 = *(const float4*)(rp + inx * 384 + 64), nkb4 = *(const float4*)(rp + inx * 384 + 128);
;         const float4 nkd4 = *(const float4*)(rp + inx * 384 + 192), nr4 = *(const float4*)(rp + inx * 384 + 256);
;         const float nv = vp[inx * 384];
;         v2f t = sA * (v2f){kk4.x, kk4.y};
;         t = sB * (v2f){kk4.z, kk4.w} + t;
;         float sa = t.x + t.y, ia = 0.f;
;         if (DUAL) {
;           v2f ti = iA * (v2f){kk4.x, kk4.y};
;           ti = iB * (v2f){kk4.z, kk4.w} + ti;
;           ia = ti.x + ti.y;
;           sa += dppf<0xB1>(sa); ia += dppf<0xB1>(ia);
;           sa += dppf<0x4E>(sa); ia += dppf<0x4E>(ia);
;           sa += dppf<0x141>(sa); ia += dppf<0x141>(ia);
;           sa += dppf<0x140>(sa); ia += dppf<0x140>(ia);
;         } else {
;           sa = sum16(sa);
;         }
;         v2f cA = sA * (v2f){w4.x, w4.y} + (v2f){kd4.x, kd4.y} * v;
;         v2f cB = sB * (v2f){w4.z, w4.w} + (v2f){kd4.z, kd4.w} * v;
;         sA = cA - (v2f){kb4.x, kb4.y} * sa;
;         sB = cB - (v2f){kb4.z, kb4.w} * sa;
;         v2f u = sA * (v2f){r4.x, r4.y};
;         u = sB * (v2f){r4.z, r4.w} + u;
;         float y = u.x + u.y, g = 0.f;
;         if (DUAL) {
;           iA = iA * (v2f){w4.x, w4.y} - (v2f){kb4.x, kb4.y} * ia;
;           iB = iB * (v2f){w4.z, w4.w} - (v2f){kb4.z, kb4.w} * ia;
;           v2f ui = iA * (v2f){r4.x, r4.y};
;           ui = iB * (v2f){r4.z, r4.w} + ui;
;           g = ui.x + ui.y;
;           y += dppf<0xB1>(y); g += dppf<0xB1>(g);
;           y += dppf<0x4E>(y); g += dppf<0x4E>(g);
;           y += dppf<0x141>(y); g += dppf<0x141>(g);
;           y += dppf<0x140>(y); g += dppf<0x140>(g);
;           if (fr == (i & 15)) gkeep = g;
;         } else {
;           y = sum16(y);
;         }
;         if (fr == (i & 15)) ykeep = y;
;         if ((i & 15) == 15) {
;           const int ii = (i & 16) + fr;
;           const int ri = (d == 0) ? ii + 1 : 32 - ii;
;           const int pi = plo - 1 + ri;
;           p.yR[((size_t)d * TOK + rowbase + pi) * 256 + h * 64 + row] = f2bf(ykeep);
	v_pk_mul_f32 v[64:65], v[60:61], v[122:123]
	v_pk_fma_f32 v[64:65], v[62:63], v[124:125], v[64:65]
	v_add_f32_e32 v64, v64, v65
	v_pk_mul_f32 v[60:61], v[60:61], v[118:119]
	v_pk_mul_f32 v[62:63], v[62:63], v[120:121]
	v_add_f32_dpp v64, v64, v64 quad_perm:[1,0,3,2] row_mask:0xf bank_mask:0xf bound_ctrl:1
	s_waitcnt lgkmcnt(8)
	v_pk_fma_f32 v[60:61], v[138:139], v[130:131], v[60:61] op_sel_hi:[0,1,1]
	v_pk_fma_f32 v[62:63], v[138:139], v[132:133], v[62:63] op_sel_hi:[0,1,1]
	v_add_f32_dpp v64, v64, v64 quad_perm:[2,3,0,1] row_mask:0xf bank_mask:0xf bound_ctrl:1
	ds_read_b128 v[122:125], v68 offset:27136
	ds_read_b128 v[118:121], v68 offset:26880
	v_add_f32_dpp v64, v64, v64 row_half_mirror row_mask:0xf bank_mask:0xf bound_ctrl:1
	ds_read_b128 v[130:133], v68 offset:27648
	ds_read_b32 v138, v69 offset:28160
	v_add_f32_dpp v64, v64, v64 row_mirror row_mask:0xf bank_mask:0xf bound_ctrl:1
	s_waitcnt lgkmcnt(11)
	v_pk_fma_f32 v[60:61], v[126:127], v[64:65], v[60:61] op_sel_hi:[1,0,1] neg_lo:[1,0,0] neg_hi:[1,0,0]
	v_pk_fma_f32 v[62:63], v[128:129], v[64:65], v[62:63] op_sel_hi:[1,0,1] neg_lo:[1,0,0] neg_hi:[1,0,0]
	ds_read_b128 v[126:129], v68 offset:27392
	s_waitcnt lgkmcnt(11)
	v_pk_mul_f32 v[66:67], v[134:135], v[60:61]
	v_pk_fma_f32 v[66:67], v[136:137], v[62:63], v[66:67]
	ds_read_b128 v[134:137], v68 offset:27904
	v_add_f32_e32 v155, v66, v67
	v_add_f32_dpp v140, v140, v140 row_shl:8 row_mask:0xf bank_mask:0x3
	v_add_f32_dpp v140, v148, v148 row_shr:8 row_mask:0xf bank_mask:0xc
	v_add_f32_dpp v141, v141, v141 row_shl:8 row_mask:0xf bank_mask:0x3
	v_add_f32_dpp v141, v149, v149 row_shr:8 row_mask:0xf bank_mask:0xc
	v_add_f32_dpp v142, v142, v142 row_shl:8 row_mask:0xf bank_mask:0x3
	v_add_f32_dpp v142, v150, v150 row_shr:8 row_mask:0xf bank_mask:0xc
	v_add_f32_dpp v143, v143, v143 row_shl:8 row_mask:0xf bank_mask:0x3
	v_add_f32_dpp v143, v151, v151 row_shr:8 row_mask:0xf bank_mask:0xc
	v_add_f32_dpp v144, v144, v144 row_shl:8 row_mask:0xf bank_mask:0x3
	v_add_f32_dpp v144, v152, v152 row_shr:8 row_mask:0xf bank_mask:0xc
	v_add_f32_dpp v145, v145, v145 row_shl:8 row_mask:0xf bank_mask:0x3
	v_add_f32_dpp v145, v153, v153 row_shr:8 row_mask:0xf bank_mask:0xc
	v_add_f32_dpp v146, v146, v146 row_shl:8 row_mask:0xf bank_mask:0x3
	v_add_f32_dpp v146, v154, v154 row_shr:8 row_mask:0xf bank_mask:0xc
	v_add_f32_dpp v147, v147, v147 row_shl:8 row_mask:0xf bank_mask:0x3
	v_add_f32_dpp v147, v155, v155 row_shr:8 row_mask:0xf bank_mask:0xc
	v_add_f32_dpp v140, v140, v140 row_shl:4 row_mask:0xf bank_mask:0x5
	v_add_f32_dpp v140, v144, v144 row_shr:4 row_mask:0xf bank_mask:0xa
	v_add_f32_dpp v141, v141, v141 row_shl:4 row_mask:0xf bank_mask:0x5
	v_add_f32_dpp v141, v145, v145 row_shr:4 row_mask:0xf bank_mask:0xa
	v_add_f32_dpp v142, v142, v142 row_shl:4 row_mask:0xf bank_mask:0x5
	v_add_f32_dpp v142, v146, v146 row_shr:4 row_mask:0xf bank_mask:0xa
	v_add_f32_dpp v143, v143, v143 row_shl:4 row_mask:0xf bank_mask:0x5
	v_add_f32_dpp v143, v147, v147 row_shr:4 row_mask:0xf bank_mask:0xa
	v_cndmask_b32_e32 v156, v140, v142, vcc
	v_cndmask_b32_e32 v157, v142, v140, vcc
	v_cndmask_b32_e32 v159, v143, v141, vcc
	v_cndmask_b32_e32 v158, v141, v143, vcc
	v_add_f32_dpp v156, v157, v156 quad_perm:[2,3,0,1] row_mask:0xf bank_mask:0xf
	v_add_f32_dpp v158, v159, v158 quad_perm:[2,3,0,1] row_mask:0xf bank_mask:0xf
	v_cndmask_b32_e64 v160, v156, v158, s[58:59]
	v_cndmask_b32_e64 v161, v158, v156, s[58:59]
	v_add_u32_e32 v72, 0x6000, v72
	v_add_u32_e32 v73, 0x6000, v73
	v_add_f32_dpp v70, v161, v160 quad_perm:[1,0,3,2] row_mask:0xf bank_mask:0xf
	v_mov_b32_e32 v68, v99
	v_mov_b32_e32 v69, v100
	v_mov_b32_e32 v77, v71
	v_add_u32_e32 v75, 1, v77
	v_sub_u32_e32 v74, 32, v77
	v_cndmask_b32_e64 v74, v74, v75, s[36:37]
	v_add_u32_e32 v74, s28, v74
	v_ashrrev_i32_e32 v75, 31, v74
	v_lshl_add_u64 v[74:75], s[20:21], 0, v[74:75]
	v_lshlrev_b64 v[74:75], 9, v[74:75]
	v_cvt_pk_bf16_f32 v76, v70, v70
	v_lshl_add_u64 v[74:75], v[90:91], 0, v[74:75]
	global_store_short v[74:75], v76, off
	v_add_u32_e32 v71, 16, v71
	s_add_i32 s50, s50, 1
	s_cmp_lg_u32 s50, 2
	s_cbranch_scc1 .Lrw_nd_loop
	s_branch .LBB0_1491
